# GEMM K-loops: removed redundant post-barrier lgkmcnt wait and no-op setprio pair from each MFMA segment
# speedup vs baseline: 1.0077x; 1.0077x over previous
.LBB0_131:
	s_add_u32 s28, s8, s10
	s_addc_u32 s29, s9, s11
	s_add_u32 s34, s28, 0x100
	s_addc_u32 s35, s29, 0
	s_add_u32 s30, s70, s10
	s_addc_u32 s31, s71, s11
	s_add_u32 s28, s28, 0x180
	s_addc_u32 s29, s29, 0
	s_add_i32 s73, 0, 0x10000
	s_add_i32 s76, 0, 0x14000
	v_add_u32_e32 v146, s73, v166
	ds_read_b128 v[148:151], v146
	ds_read_b128 v[152:155], v146 offset:1024
	ds_read_b128 v[156:159], v146 offset:2048
	ds_read_b128 v[160:163], v146 offset:3072
	v_add_u32_e32 v146, s76, v166
	ds_read_b128 v[172:175], v146
	ds_read_b128 v[176:179], v146 offset:1024
	ds_read_b128 v[180:183], v146 offset:2048
	ds_read_b128 v[184:187], v146 offset:3072
	s_cmpk_eq_i32 s10, 0x700
	s_cselect_b32 s29, s69, s29
	s_cselect_b32 s28, s68, s28
	s_cselect_b32 s31, s21, s31
	s_cselect_b32 s30, s59, s30
	s_cselect_b32 s35, s23, s35
	s_cselect_b32 s34, s58, s34
	v_lshl_add_u64 v[164:165], v[142:143], 0, s[10:11]
	s_add_i32 m0, s41, 0xc000
	ds_read_b128 v[188:191], v171
	ds_read_b128 v[202:205], v171 offset:1024
	ds_read_b128 v[206:209], v171 offset:2048
	ds_read_b128 v[210:213], v171 offset:3072
	ds_read_b128 v[214:217], v171 offset:4096
	ds_read_b128 v[218:221], v171 offset:5120
	ds_read_b128 v[222:225], v171 offset:6144
	ds_read_b128 v[226:229], v171 offset:7168
	global_load_lds_dwordx4 v[164:165], off
	v_lshl_add_u64 v[164:165], v[144:145], 0, s[10:11]
	s_add_i32 m0, s41, 0xe000
	s_nop 0
	global_load_lds_dwordx4 v[164:165], off
	s_waitcnt vmcnt(8)
	s_waitcnt lgkmcnt(0)
	s_barrier
	s_setprio 1
	v_mfma_f32_16x16x32_bf16 v[126:129], v[148:151], v[188:191], v[126:129]
	v_mfma_f32_16x16x32_bf16 v[122:125], v[156:159], v[188:191], v[122:125]
	v_mfma_f32_16x16x32_bf16 v[110:113], v[148:151], v[206:209], v[110:113]
	v_mfma_f32_16x16x32_bf16 v[106:109], v[156:159], v[206:209], v[106:109]
	v_mfma_f32_16x16x32_bf16 v[94:97], v[148:151], v[214:217], v[94:97]
	v_mfma_f32_16x16x32_bf16 v[90:93], v[156:159], v[214:217], v[90:93]
	v_mfma_f32_16x16x32_bf16 v[78:81], v[148:151], v[222:225], v[78:81]
	v_mfma_f32_16x16x32_bf16 v[74:77], v[156:159], v[222:225], v[74:77]
	v_mfma_f32_16x16x32_bf16 v[126:129], v[152:155], v[202:205], v[126:129]
	v_mfma_f32_16x16x32_bf16 v[122:125], v[160:163], v[202:205], v[122:125]
	v_mfma_f32_16x16x32_bf16 v[110:113], v[152:155], v[210:213], v[110:113]
	v_mfma_f32_16x16x32_bf16 v[106:109], v[160:163], v[210:213], v[106:109]
	v_mfma_f32_16x16x32_bf16 v[94:97], v[152:155], v[218:221], v[94:97]
	v_mfma_f32_16x16x32_bf16 v[90:93], v[160:163], v[218:221], v[90:93]
	v_mfma_f32_16x16x32_bf16 v[78:81], v[152:155], v[226:229], v[78:81]
	v_mfma_f32_16x16x32_bf16 v[74:77], v[160:163], v[226:229], v[74:77]
	v_mfma_f32_16x16x32_bf16 v[118:121], v[172:175], v[188:191], v[118:121]
	v_mfma_f32_16x16x32_bf16 v[114:117], v[180:183], v[188:191], v[114:117]
	v_mfma_f32_16x16x32_bf16 v[102:105], v[172:175], v[206:209], v[102:105]
	v_mfma_f32_16x16x32_bf16 v[98:101], v[180:183], v[206:209], v[98:101]
	v_mfma_f32_16x16x32_bf16 v[86:89], v[172:175], v[214:217], v[86:89]
	v_mfma_f32_16x16x32_bf16 v[82:85], v[180:183], v[214:217], v[82:85]
	v_mfma_f32_16x16x32_bf16 v[70:73], v[172:175], v[222:225], v[70:73]
	v_mfma_f32_16x16x32_bf16 v[66:69], v[180:183], v[222:225], v[66:69]
	v_mfma_f32_16x16x32_bf16 v[118:121], v[176:179], v[202:205], v[118:121]
	v_mfma_f32_16x16x32_bf16 v[114:117], v[184:187], v[202:205], v[114:117]
	v_mfma_f32_16x16x32_bf16 v[102:105], v[176:179], v[210:213], v[102:105]
	v_mfma_f32_16x16x32_bf16 v[98:101], v[184:187], v[210:213], v[98:101]
	v_mfma_f32_16x16x32_bf16 v[86:89], v[176:179], v[218:221], v[86:89]
	v_mfma_f32_16x16x32_bf16 v[82:85], v[184:187], v[218:221], v[82:85]
	v_mfma_f32_16x16x32_bf16 v[70:73], v[176:179], v[226:229], v[70:73]
	v_mfma_f32_16x16x32_bf16 v[66:69], v[184:187], v[226:229], v[66:69]
	s_setprio 0
	s_barrier
	s_add_i32 s73, s73, s40
	v_lshl_add_u64 v[164:165], s[30:31], 0, v[134:135]
	s_mov_b32 m0, s73
	ds_read_b128 v[188:191], v171 offset:16384
	ds_read_b128 v[202:205], v171 offset:17408
	ds_read_b128 v[206:209], v171 offset:18432
	ds_read_b128 v[210:213], v171 offset:19456
	ds_read_b128 v[214:217], v171 offset:20480
	ds_read_b128 v[218:221], v171 offset:21504
	ds_read_b128 v[222:225], v171 offset:22528
	ds_read_b128 v[226:229], v171 offset:23552
	global_load_lds_dwordx4 v[164:165], off
	s_add_i32 m0, s73, 0x2000
	s_add_u32 s74, s30, 0x40000
	v_lshl_add_u64 v[192:193], s[30:31], 0, v[130:131]
	s_addc_u32 s75, s31, 0
	s_add_i32 s73, s76, s40
	global_load_lds_dwordx4 v[192:193], off
	v_lshl_add_u64 v[194:195], s[74:75], 0, v[134:135]
	s_mov_b32 m0, s73
	s_nop 0
	global_load_lds_dwordx4 v[194:195], off
	v_lshl_add_u64 v[194:195], s[74:75], 0, v[130:131]
	s_add_i32 m0, s73, 0x2000
	s_nop 0
	global_load_lds_dwordx4 v[194:195], off
	v_lshl_add_u64 v[194:195], s[34:35], 0, v[136:137]
	s_mov_b32 m0, s41
	s_nop 0
	global_load_lds_dwordx4 v[194:195], off
	v_lshl_add_u64 v[194:195], s[34:35], 0, v[132:133]
	s_mov_b32 m0, s42
	s_nop 0
	global_load_lds_dwordx4 v[194:195], off
	s_waitcnt vmcnt(8)
	s_waitcnt lgkmcnt(0)
	s_barrier
	s_setprio 1
	v_mfma_f32_16x16x32_bf16 v[62:65], v[148:151], v[188:191], v[62:65]
	v_mfma_f32_16x16x32_bf16 v[58:61], v[156:159], v[188:191], v[58:61]
	v_mfma_f32_16x16x32_bf16 v[46:49], v[148:151], v[206:209], v[46:49]
	v_mfma_f32_16x16x32_bf16 v[42:45], v[156:159], v[206:209], v[42:45]
	v_mfma_f32_16x16x32_bf16 v[30:33], v[148:151], v[214:217], v[30:33]
	v_mfma_f32_16x16x32_bf16 v[26:29], v[156:159], v[214:217], v[26:29]
	v_mfma_f32_16x16x32_bf16 v[14:17], v[148:151], v[222:225], v[14:17]
	v_mfma_f32_16x16x32_bf16 v[10:13], v[156:159], v[222:225], v[10:13]
	v_mfma_f32_16x16x32_bf16 v[62:65], v[152:155], v[202:205], v[62:65]
	v_mfma_f32_16x16x32_bf16 v[58:61], v[160:163], v[202:205], v[58:61]
	v_mfma_f32_16x16x32_bf16 v[46:49], v[152:155], v[210:213], v[46:49]
	v_mfma_f32_16x16x32_bf16 v[42:45], v[160:163], v[210:213], v[42:45]
	v_mfma_f32_16x16x32_bf16 v[30:33], v[152:155], v[218:221], v[30:33]
	v_mfma_f32_16x16x32_bf16 v[26:29], v[160:163], v[218:221], v[26:29]
	v_mfma_f32_16x16x32_bf16 v[14:17], v[152:155], v[226:229], v[14:17]
	v_mfma_f32_16x16x32_bf16 v[10:13], v[160:163], v[226:229], v[10:13]
	v_mfma_f32_16x16x32_bf16 v[54:57], v[172:175], v[188:191], v[54:57]
	v_mfma_f32_16x16x32_bf16 v[50:53], v[180:183], v[188:191], v[50:53]
	v_mfma_f32_16x16x32_bf16 v[38:41], v[172:175], v[206:209], v[38:41]
	v_mfma_f32_16x16x32_bf16 v[34:37], v[180:183], v[206:209], v[34:37]
	v_mfma_f32_16x16x32_bf16 v[22:25], v[172:175], v[214:217], v[22:25]
	v_mfma_f32_16x16x32_bf16 v[18:21], v[180:183], v[214:217], v[18:21]
	v_mfma_f32_16x16x32_bf16 v[6:9], v[172:175], v[222:225], v[6:9]
	v_mfma_f32_16x16x32_bf16 v[2:5], v[180:183], v[222:225], v[2:5]
	v_mfma_f32_16x16x32_bf16 v[54:57], v[176:179], v[202:205], v[54:57]
	v_mfma_f32_16x16x32_bf16 v[50:53], v[184:187], v[202:205], v[50:53]
	v_mfma_f32_16x16x32_bf16 v[38:41], v[176:179], v[210:213], v[38:41]
	v_mfma_f32_16x16x32_bf16 v[34:37], v[184:187], v[210:213], v[34:37]
	v_mfma_f32_16x16x32_bf16 v[22:25], v[176:179], v[218:221], v[22:25]
	v_mfma_f32_16x16x32_bf16 v[18:21], v[184:187], v[218:221], v[18:21]
	v_mfma_f32_16x16x32_bf16 v[6:9], v[176:179], v[226:229], v[6:9]
	v_mfma_f32_16x16x32_bf16 v[2:5], v[184:187], v[226:229], v[2:5]
	s_setprio 0
	s_barrier
	s_add_i32 s73, 0, 0x18000
	v_add_u32_e32 v146, s73, v166
	s_add_i32 s74, 0, 0x1c000
	ds_read_b128 v[148:151], v146
	ds_read_b128 v[152:155], v146 offset:1024
	ds_read_b128 v[156:159], v146 offset:2048
	ds_read_b128 v[160:163], v146 offset:3072
	v_add_u32_e32 v146, s74, v166
	ds_read_b128 v[172:175], v146
	ds_read_b128 v[176:179], v146 offset:1024
	ds_read_b128 v[180:183], v146 offset:2048
	ds_read_b128 v[184:187], v146 offset:3072
	s_add_u32 s34, s34, 0x40000
	s_addc_u32 s35, s35, 0
	s_mov_b32 m0, s43
	v_lshl_add_u64 v[194:195], s[34:35], 0, v[136:137]
	ds_read_b128 v[188:191], v171 offset:32768
	ds_read_b128 v[202:205], v171 offset:33792
	ds_read_b128 v[206:209], v171 offset:34816
	ds_read_b128 v[210:213], v171 offset:35840
	ds_read_b128 v[214:217], v171 offset:36864
	ds_read_b128 v[218:221], v171 offset:37888
	ds_read_b128 v[222:225], v171 offset:38912
	ds_read_b128 v[226:229], v171 offset:39936
	global_load_lds_dwordx4 v[194:195], off
	v_lshl_add_u64 v[194:195], s[34:35], 0, v[132:133]
	s_mov_b32 m0, s44
	s_nop 0
	global_load_lds_dwordx4 v[194:195], off
	s_waitcnt vmcnt(8)
	s_waitcnt lgkmcnt(0)
	s_barrier
	s_setprio 1
	v_mfma_f32_16x16x32_bf16 v[126:129], v[148:151], v[188:191], v[126:129]
	v_mfma_f32_16x16x32_bf16 v[122:125], v[156:159], v[188:191], v[122:125]
	v_mfma_f32_16x16x32_bf16 v[110:113], v[148:151], v[206:209], v[110:113]
	v_mfma_f32_16x16x32_bf16 v[106:109], v[156:159], v[206:209], v[106:109]
	v_mfma_f32_16x16x32_bf16 v[94:97], v[148:151], v[214:217], v[94:97]
	v_mfma_f32_16x16x32_bf16 v[90:93], v[156:159], v[214:217], v[90:93]
	v_mfma_f32_16x16x32_bf16 v[78:81], v[148:151], v[222:225], v[78:81]
	v_mfma_f32_16x16x32_bf16 v[74:77], v[156:159], v[222:225], v[74:77]
	v_mfma_f32_16x16x32_bf16 v[126:129], v[152:155], v[202:205], v[126:129]
	v_mfma_f32_16x16x32_bf16 v[122:125], v[160:163], v[202:205], v[122:125]
	v_mfma_f32_16x16x32_bf16 v[110:113], v[152:155], v[210:213], v[110:113]
	v_mfma_f32_16x16x32_bf16 v[106:109], v[160:163], v[210:213], v[106:109]
	v_mfma_f32_16x16x32_bf16 v[94:97], v[152:155], v[218:221], v[94:97]
	v_mfma_f32_16x16x32_bf16 v[90:93], v[160:163], v[218:221], v[90:93]
	v_mfma_f32_16x16x32_bf16 v[78:81], v[152:155], v[226:229], v[78:81]
	v_mfma_f32_16x16x32_bf16 v[74:77], v[160:163], v[226:229], v[74:77]
	v_mfma_f32_16x16x32_bf16 v[118:121], v[172:175], v[188:191], v[118:121]
	v_mfma_f32_16x16x32_bf16 v[114:117], v[180:183], v[188:191], v[114:117]
	v_mfma_f32_16x16x32_bf16 v[102:105], v[172:175], v[206:209], v[102:105]
	v_mfma_f32_16x16x32_bf16 v[98:101], v[180:183], v[206:209], v[98:101]
	v_mfma_f32_16x16x32_bf16 v[86:89], v[172:175], v[214:217], v[86:89]
	v_mfma_f32_16x16x32_bf16 v[82:85], v[180:183], v[214:217], v[82:85]
	v_mfma_f32_16x16x32_bf16 v[70:73], v[172:175], v[222:225], v[70:73]
	v_mfma_f32_16x16x32_bf16 v[66:69], v[180:183], v[222:225], v[66:69]
	v_mfma_f32_16x16x32_bf16 v[118:121], v[176:179], v[202:205], v[118:121]
	v_mfma_f32_16x16x32_bf16 v[114:117], v[184:187], v[202:205], v[114:117]
	v_mfma_f32_16x16x32_bf16 v[102:105], v[176:179], v[210:213], v[102:105]
	v_mfma_f32_16x16x32_bf16 v[98:101], v[184:187], v[210:213], v[98:101]
	v_mfma_f32_16x16x32_bf16 v[86:89], v[176:179], v[218:221], v[86:89]
	v_mfma_f32_16x16x32_bf16 v[82:85], v[184:187], v[218:221], v[82:85]
	v_mfma_f32_16x16x32_bf16 v[70:73], v[176:179], v[226:229], v[70:73]
	v_mfma_f32_16x16x32_bf16 v[66:69], v[184:187], v[226:229], v[66:69]
	s_setprio 0
	s_barrier
	s_add_i32 s34, s73, s40
	v_lshl_add_u64 v[164:165], v[164:165], 0, s[90:91]
	s_mov_b32 m0, s34
	ds_read_b128 v[188:191], v171 offset:49152
	ds_read_b128 v[202:205], v171 offset:50176
	ds_read_b128 v[206:209], v171 offset:51200
	ds_read_b128 v[210:213], v171 offset:52224
	ds_read_b128 v[214:217], v171 offset:53248
	ds_read_b128 v[218:221], v171 offset:54272
	ds_read_b128 v[222:225], v171 offset:55296
	ds_read_b128 v[226:229], v171 offset:56320
	global_load_lds_dwordx4 v[164:165], off
	s_add_i32 m0, s34, 0x2000
	s_add_u32 s30, s30, 0x40080
	v_lshl_add_u64 v[164:165], v[192:193], 0, s[90:91]
	s_addc_u32 s31, s31, 0
	s_add_i32 s34, s74, s40
	global_load_lds_dwordx4 v[164:165], off
	v_lshl_add_u64 v[164:165], s[30:31], 0, v[134:135]
	s_mov_b32 m0, s34
	s_nop 0
	global_load_lds_dwordx4 v[164:165], off
	v_lshl_add_u64 v[164:165], s[30:31], 0, v[130:131]
	s_add_i32 m0, s34, 0x2000
	s_nop 0
	global_load_lds_dwordx4 v[164:165], off
	v_lshl_add_u64 v[164:165], s[28:29], 0, v[136:137]
	s_mov_b32 m0, s45
	s_nop 0
	global_load_lds_dwordx4 v[164:165], off
	v_lshl_add_u64 v[164:165], s[28:29], 0, v[132:133]
	s_mov_b32 m0, s51
	s_nop 0
	global_load_lds_dwordx4 v[164:165], off
	s_waitcnt vmcnt(8)
	s_waitcnt lgkmcnt(0)
	s_barrier
	s_setprio 1
	v_mfma_f32_16x16x32_bf16 v[62:65], v[148:151], v[188:191], v[62:65]
	v_mfma_f32_16x16x32_bf16 v[58:61], v[156:159], v[188:191], v[58:61]
	v_mfma_f32_16x16x32_bf16 v[46:49], v[148:151], v[206:209], v[46:49]
	v_mfma_f32_16x16x32_bf16 v[42:45], v[156:159], v[206:209], v[42:45]
	v_mfma_f32_16x16x32_bf16 v[30:33], v[148:151], v[214:217], v[30:33]
	v_mfma_f32_16x16x32_bf16 v[26:29], v[156:159], v[214:217], v[26:29]
	v_mfma_f32_16x16x32_bf16 v[14:17], v[148:151], v[222:225], v[14:17]
	v_mfma_f32_16x16x32_bf16 v[10:13], v[156:159], v[222:225], v[10:13]
	v_mfma_f32_16x16x32_bf16 v[62:65], v[152:155], v[202:205], v[62:65]
	v_mfma_f32_16x16x32_bf16 v[58:61], v[160:163], v[202:205], v[58:61]
	v_mfma_f32_16x16x32_bf16 v[46:49], v[152:155], v[210:213], v[46:49]
	v_mfma_f32_16x16x32_bf16 v[42:45], v[160:163], v[210:213], v[42:45]
	v_mfma_f32_16x16x32_bf16 v[30:33], v[152:155], v[218:221], v[30:33]
	v_mfma_f32_16x16x32_bf16 v[26:29], v[160:163], v[218:221], v[26:29]
	v_mfma_f32_16x16x32_bf16 v[14:17], v[152:155], v[226:229], v[14:17]
	v_mfma_f32_16x16x32_bf16 v[10:13], v[160:163], v[226:229], v[10:13]
	v_mfma_f32_16x16x32_bf16 v[54:57], v[172:175], v[188:191], v[54:57]
	v_mfma_f32_16x16x32_bf16 v[50:53], v[180:183], v[188:191], v[50:53]
	v_mfma_f32_16x16x32_bf16 v[38:41], v[172:175], v[206:209], v[38:41]
	v_mfma_f32_16x16x32_bf16 v[34:37], v[180:183], v[206:209], v[34:37]
	v_mfma_f32_16x16x32_bf16 v[22:25], v[172:175], v[214:217], v[22:25]
	v_mfma_f32_16x16x32_bf16 v[18:21], v[180:183], v[214:217], v[18:21]
	v_mfma_f32_16x16x32_bf16 v[6:9], v[172:175], v[222:225], v[6:9]
	v_mfma_f32_16x16x32_bf16 v[2:5], v[180:183], v[222:225], v[2:5]
	v_mfma_f32_16x16x32_bf16 v[54:57], v[176:179], v[202:205], v[54:57]
	v_mfma_f32_16x16x32_bf16 v[50:53], v[184:187], v[202:205], v[50:53]
	v_mfma_f32_16x16x32_bf16 v[38:41], v[176:179], v[210:213], v[38:41]
	v_mfma_f32_16x16x32_bf16 v[34:37], v[184:187], v[210:213], v[34:37]
	v_mfma_f32_16x16x32_bf16 v[22:25], v[176:179], v[218:221], v[22:25]
	v_mfma_f32_16x16x32_bf16 v[18:21], v[184:187], v[218:221], v[18:21]
	v_mfma_f32_16x16x32_bf16 v[6:9], v[176:179], v[226:229], v[6:9]
	v_mfma_f32_16x16x32_bf16 v[2:5], v[184:187], v[226:229], v[2:5]
	s_setprio 0
	s_barrier
	s_add_i32 s72, s72, 2
	s_add_u32 s10, s10, 0x100
	s_addc_u32 s11, s11, 0
	s_cmp_gt_u32 s72, 13
	s_cbranch_scc0 .LBB0_131
	s_and_b64 vcc, exec, s[18:19]
	s_cbranch_vccz .LBB0_134
	s_barrier

.LBB0_345:
	s_add_u32 s34, s28, s30
	s_addc_u32 s35, s29, s31
	s_add_u32 s38, s34, 0x100
	s_addc_u32 s39, s35, 0
	s_add_u32 s36, s75, s30
	s_addc_u32 s37, s76, s31
	s_add_u32 s34, s34, 0x180
	s_addc_u32 s35, s35, 0
	s_add_i32 s85, 0, 0x10000
	s_add_i32 vcc_lo, 0, 0x14000
	v_add_u32_e32 v0, s85, v152
	ds_read_b128 v[148:151], v0
	ds_read_b128 v[154:157], v0 offset:1024
	ds_read_b128 v[158:161], v0 offset:2048
	ds_read_b128 v[162:165], v0 offset:3072
	v_add_u32_e32 v0, vcc_lo, v152
	ds_read_b128 v[166:169], v0
	ds_read_b128 v[170:173], v0 offset:1024
	ds_read_b128 v[174:177], v0 offset:2048
	ds_read_b128 v[178:181], v0 offset:3072
	s_cmpk_eq_i32 s30, 0x700
	s_cselect_b32 s35, s74, s35
	s_cselect_b32 s34, s73, s34
	s_cselect_b32 s37, s21, s37
	s_cselect_b32 s36, s72, s36
	s_cselect_b32 s39, s23, s39
	s_cselect_b32 s38, s71, s38
	v_lshl_add_u64 v[194:195], v[144:145], 0, s[30:31]
	s_add_i32 m0, s45, 0xc000
	ds_read_b128 v[182:185], v153
	ds_read_b128 v[186:189], v153 offset:1024
	ds_read_b128 v[190:193], v153 offset:2048
	ds_read_b128 v[202:205], v153 offset:3072
	ds_read_b128 v[206:209], v153 offset:4096
	ds_read_b128 v[210:213], v153 offset:5120
	ds_read_b128 v[214:217], v153 offset:6144
	ds_read_b128 v[218:221], v153 offset:7168
	global_load_lds_dwordx4 v[194:195], off
	v_lshl_add_u64 v[194:195], v[146:147], 0, s[30:31]
	s_add_i32 m0, s45, 0xe000
	s_nop 0
	global_load_lds_dwordx4 v[194:195], off
	s_waitcnt vmcnt(8)
	s_waitcnt lgkmcnt(0)
	s_barrier
	s_setprio 1
	v_mfma_f32_16x16x32_bf16 v[126:129], v[148:151], v[182:185], v[126:129]
	v_mfma_f32_16x16x32_bf16 v[122:125], v[158:161], v[182:185], v[122:125]
	v_mfma_f32_16x16x32_bf16 v[110:113], v[148:151], v[190:193], v[110:113]
	v_mfma_f32_16x16x32_bf16 v[106:109], v[158:161], v[190:193], v[106:109]
	v_mfma_f32_16x16x32_bf16 v[94:97], v[148:151], v[206:209], v[94:97]
	v_mfma_f32_16x16x32_bf16 v[90:93], v[158:161], v[206:209], v[90:93]
	v_mfma_f32_16x16x32_bf16 v[78:81], v[148:151], v[214:217], v[78:81]
	v_mfma_f32_16x16x32_bf16 v[74:77], v[158:161], v[214:217], v[74:77]
	v_mfma_f32_16x16x32_bf16 v[126:129], v[154:157], v[186:189], v[126:129]
	v_mfma_f32_16x16x32_bf16 v[122:125], v[162:165], v[186:189], v[122:125]
	v_mfma_f32_16x16x32_bf16 v[110:113], v[154:157], v[202:205], v[110:113]
	v_mfma_f32_16x16x32_bf16 v[106:109], v[162:165], v[202:205], v[106:109]
	v_mfma_f32_16x16x32_bf16 v[94:97], v[154:157], v[210:213], v[94:97]
	v_mfma_f32_16x16x32_bf16 v[90:93], v[162:165], v[210:213], v[90:93]
	v_mfma_f32_16x16x32_bf16 v[78:81], v[154:157], v[218:221], v[78:81]
	v_mfma_f32_16x16x32_bf16 v[74:77], v[162:165], v[218:221], v[74:77]
	v_mfma_f32_16x16x32_bf16 v[118:121], v[166:169], v[182:185], v[118:121]
	v_mfma_f32_16x16x32_bf16 v[114:117], v[174:177], v[182:185], v[114:117]
	v_mfma_f32_16x16x32_bf16 v[102:105], v[166:169], v[190:193], v[102:105]
	v_mfma_f32_16x16x32_bf16 v[98:101], v[174:177], v[190:193], v[98:101]
	v_mfma_f32_16x16x32_bf16 v[86:89], v[166:169], v[206:209], v[86:89]
	v_mfma_f32_16x16x32_bf16 v[82:85], v[174:177], v[206:209], v[82:85]
	v_mfma_f32_16x16x32_bf16 v[70:73], v[166:169], v[214:217], v[70:73]
	v_mfma_f32_16x16x32_bf16 v[66:69], v[174:177], v[214:217], v[66:69]
	v_mfma_f32_16x16x32_bf16 v[118:121], v[170:173], v[186:189], v[118:121]
	v_mfma_f32_16x16x32_bf16 v[114:117], v[178:181], v[186:189], v[114:117]
	v_mfma_f32_16x16x32_bf16 v[102:105], v[170:173], v[202:205], v[102:105]
	v_mfma_f32_16x16x32_bf16 v[98:101], v[178:181], v[202:205], v[98:101]
	v_mfma_f32_16x16x32_bf16 v[86:89], v[170:173], v[210:213], v[86:89]
	v_mfma_f32_16x16x32_bf16 v[82:85], v[178:181], v[210:213], v[82:85]
	v_mfma_f32_16x16x32_bf16 v[70:73], v[170:173], v[218:221], v[70:73]
	v_mfma_f32_16x16x32_bf16 v[66:69], v[178:181], v[218:221], v[66:69]
	s_setprio 0
	s_barrier
	s_add_i32 s85, s85, s44
	v_lshl_add_u64 v[194:195], s[36:37], 0, v[134:135]
	s_mov_b32 m0, s85
	ds_read_b128 v[182:185], v153 offset:16384
	ds_read_b128 v[186:189], v153 offset:17408
	ds_read_b128 v[190:193], v153 offset:18432
	ds_read_b128 v[202:205], v153 offset:19456
	ds_read_b128 v[206:209], v153 offset:20480
	ds_read_b128 v[210:213], v153 offset:21504
	ds_read_b128 v[214:217], v153 offset:22528
	ds_read_b128 v[218:221], v153 offset:23552
	global_load_lds_dwordx4 v[194:195], off
	s_add_i32 m0, s85, 0x2000
	s_add_u32 s86, s36, 0x40000
	v_lshl_add_u64 v[198:199], s[36:37], 0, v[130:131]
	s_addc_u32 s87, s37, 0
	s_add_i32 s85, vcc_lo, s44
	global_load_lds_dwordx4 v[198:199], off
	v_lshl_add_u64 v[222:223], s[86:87], 0, v[134:135]
	s_mov_b32 m0, s85
	s_nop 0
	global_load_lds_dwordx4 v[222:223], off
	v_lshl_add_u64 v[222:223], s[86:87], 0, v[130:131]
	s_add_i32 m0, s85, 0x2000
	s_nop 0
	global_load_lds_dwordx4 v[222:223], off
	v_lshl_add_u64 v[222:223], s[38:39], 0, v[136:137]
	s_mov_b32 m0, s45
	s_nop 0
	global_load_lds_dwordx4 v[222:223], off
	v_lshl_add_u64 v[222:223], s[38:39], 0, v[132:133]
	s_mov_b32 m0, s51
	s_nop 0
	global_load_lds_dwordx4 v[222:223], off
	s_waitcnt vmcnt(8)
	s_waitcnt lgkmcnt(0)
	s_barrier
	s_setprio 1
	v_mfma_f32_16x16x32_bf16 v[62:65], v[148:151], v[182:185], v[62:65]
	v_mfma_f32_16x16x32_bf16 v[58:61], v[158:161], v[182:185], v[58:61]
	v_mfma_f32_16x16x32_bf16 v[46:49], v[148:151], v[190:193], v[46:49]
	v_mfma_f32_16x16x32_bf16 v[42:45], v[158:161], v[190:193], v[42:45]
	v_mfma_f32_16x16x32_bf16 v[30:33], v[148:151], v[206:209], v[30:33]
	v_mfma_f32_16x16x32_bf16 v[26:29], v[158:161], v[206:209], v[26:29]
	v_mfma_f32_16x16x32_bf16 v[14:17], v[148:151], v[214:217], v[14:17]
	v_mfma_f32_16x16x32_bf16 v[10:13], v[158:161], v[214:217], v[10:13]
	v_mfma_f32_16x16x32_bf16 v[62:65], v[154:157], v[186:189], v[62:65]
	v_mfma_f32_16x16x32_bf16 v[58:61], v[162:165], v[186:189], v[58:61]
	v_mfma_f32_16x16x32_bf16 v[46:49], v[154:157], v[202:205], v[46:49]
	v_mfma_f32_16x16x32_bf16 v[42:45], v[162:165], v[202:205], v[42:45]
	v_mfma_f32_16x16x32_bf16 v[30:33], v[154:157], v[210:213], v[30:33]
	v_mfma_f32_16x16x32_bf16 v[26:29], v[162:165], v[210:213], v[26:29]
	v_mfma_f32_16x16x32_bf16 v[14:17], v[154:157], v[218:221], v[14:17]
	v_mfma_f32_16x16x32_bf16 v[10:13], v[162:165], v[218:221], v[10:13]
	v_mfma_f32_16x16x32_bf16 v[54:57], v[166:169], v[182:185], v[54:57]
	v_mfma_f32_16x16x32_bf16 v[50:53], v[174:177], v[182:185], v[50:53]
	v_mfma_f32_16x16x32_bf16 v[38:41], v[166:169], v[190:193], v[38:41]
	v_mfma_f32_16x16x32_bf16 v[34:37], v[174:177], v[190:193], v[34:37]
	v_mfma_f32_16x16x32_bf16 v[22:25], v[166:169], v[206:209], v[22:25]
	v_mfma_f32_16x16x32_bf16 v[18:21], v[174:177], v[206:209], v[18:21]
	v_mfma_f32_16x16x32_bf16 v[6:9], v[166:169], v[214:217], v[6:9]
	v_mfma_f32_16x16x32_bf16 v[2:5], v[174:177], v[214:217], v[2:5]
	v_mfma_f32_16x16x32_bf16 v[54:57], v[170:173], v[186:189], v[54:57]
	v_mfma_f32_16x16x32_bf16 v[50:53], v[178:181], v[186:189], v[50:53]
	v_mfma_f32_16x16x32_bf16 v[38:41], v[170:173], v[202:205], v[38:41]
	v_mfma_f32_16x16x32_bf16 v[34:37], v[178:181], v[202:205], v[34:37]
	v_mfma_f32_16x16x32_bf16 v[22:25], v[170:173], v[210:213], v[22:25]
	v_mfma_f32_16x16x32_bf16 v[18:21], v[178:181], v[210:213], v[18:21]
	v_mfma_f32_16x16x32_bf16 v[6:9], v[170:173], v[218:221], v[6:9]
	v_mfma_f32_16x16x32_bf16 v[2:5], v[178:181], v[218:221], v[2:5]
	s_setprio 0
	s_barrier
	s_add_i32 s85, 0, 0x18000
	v_add_u32_e32 v0, s85, v152
	s_add_i32 s86, 0, 0x1c000
	ds_read_b128 v[148:151], v0
	ds_read_b128 v[154:157], v0 offset:1024
	ds_read_b128 v[158:161], v0 offset:2048
	ds_read_b128 v[162:165], v0 offset:3072
	v_add_u32_e32 v0, s86, v152
	ds_read_b128 v[166:169], v0
	ds_read_b128 v[170:173], v0 offset:1024
	ds_read_b128 v[174:177], v0 offset:2048
	ds_read_b128 v[178:181], v0 offset:3072
	s_add_u32 s38, s38, 0x40000
	s_addc_u32 s39, s39, 0
	s_mov_b32 m0, s55
	v_lshl_add_u64 v[222:223], s[38:39], 0, v[136:137]
	ds_read_b128 v[182:185], v153 offset:32768
	ds_read_b128 v[186:189], v153 offset:33792
	ds_read_b128 v[190:193], v153 offset:34816
	ds_read_b128 v[202:205], v153 offset:35840
	ds_read_b128 v[206:209], v153 offset:36864
	ds_read_b128 v[210:213], v153 offset:37888
	ds_read_b128 v[214:217], v153 offset:38912
	ds_read_b128 v[218:221], v153 offset:39936
	global_load_lds_dwordx4 v[222:223], off
	v_lshl_add_u64 v[222:223], s[38:39], 0, v[132:133]
	s_mov_b32 m0, s56
	s_nop 0
	global_load_lds_dwordx4 v[222:223], off
	s_waitcnt vmcnt(8)
	s_waitcnt lgkmcnt(0)
	s_barrier
	s_setprio 1
	v_mfma_f32_16x16x32_bf16 v[126:129], v[148:151], v[182:185], v[126:129]
	v_mfma_f32_16x16x32_bf16 v[122:125], v[158:161], v[182:185], v[122:125]
	v_mfma_f32_16x16x32_bf16 v[110:113], v[148:151], v[190:193], v[110:113]
	v_mfma_f32_16x16x32_bf16 v[106:109], v[158:161], v[190:193], v[106:109]
	v_mfma_f32_16x16x32_bf16 v[94:97], v[148:151], v[206:209], v[94:97]
	v_mfma_f32_16x16x32_bf16 v[90:93], v[158:161], v[206:209], v[90:93]
	v_mfma_f32_16x16x32_bf16 v[78:81], v[148:151], v[214:217], v[78:81]
	v_mfma_f32_16x16x32_bf16 v[74:77], v[158:161], v[214:217], v[74:77]
	v_mfma_f32_16x16x32_bf16 v[126:129], v[154:157], v[186:189], v[126:129]
	v_mfma_f32_16x16x32_bf16 v[122:125], v[162:165], v[186:189], v[122:125]
	v_mfma_f32_16x16x32_bf16 v[110:113], v[154:157], v[202:205], v[110:113]
	v_mfma_f32_16x16x32_bf16 v[106:109], v[162:165], v[202:205], v[106:109]
	v_mfma_f32_16x16x32_bf16 v[94:97], v[154:157], v[210:213], v[94:97]
	v_mfma_f32_16x16x32_bf16 v[90:93], v[162:165], v[210:213], v[90:93]
	v_mfma_f32_16x16x32_bf16 v[78:81], v[154:157], v[218:221], v[78:81]
	v_mfma_f32_16x16x32_bf16 v[74:77], v[162:165], v[218:221], v[74:77]
	v_mfma_f32_16x16x32_bf16 v[118:121], v[166:169], v[182:185], v[118:121]
	v_mfma_f32_16x16x32_bf16 v[114:117], v[174:177], v[182:185], v[114:117]
	v_mfma_f32_16x16x32_bf16 v[102:105], v[166:169], v[190:193], v[102:105]
	v_mfma_f32_16x16x32_bf16 v[98:101], v[174:177], v[190:193], v[98:101]
	v_mfma_f32_16x16x32_bf16 v[86:89], v[166:169], v[206:209], v[86:89]
	v_mfma_f32_16x16x32_bf16 v[82:85], v[174:177], v[206:209], v[82:85]
	v_mfma_f32_16x16x32_bf16 v[70:73], v[166:169], v[214:217], v[70:73]
	v_mfma_f32_16x16x32_bf16 v[66:69], v[174:177], v[214:217], v[66:69]
	v_mfma_f32_16x16x32_bf16 v[118:121], v[170:173], v[186:189], v[118:121]
	v_mfma_f32_16x16x32_bf16 v[114:117], v[178:181], v[186:189], v[114:117]
	v_mfma_f32_16x16x32_bf16 v[102:105], v[170:173], v[202:205], v[102:105]
	v_mfma_f32_16x16x32_bf16 v[98:101], v[178:181], v[202:205], v[98:101]
	v_mfma_f32_16x16x32_bf16 v[86:89], v[170:173], v[210:213], v[86:89]
	v_mfma_f32_16x16x32_bf16 v[82:85], v[178:181], v[210:213], v[82:85]
	v_mfma_f32_16x16x32_bf16 v[70:73], v[170:173], v[218:221], v[70:73]
	v_mfma_f32_16x16x32_bf16 v[66:69], v[178:181], v[218:221], v[66:69]
	s_setprio 0
	s_barrier
	s_add_i32 s38, s85, s44
	v_lshl_add_u64 v[194:195], v[194:195], 0, s[90:91]
	s_mov_b32 m0, s38
	ds_read_b128 v[182:185], v153 offset:49152
	ds_read_b128 v[186:189], v153 offset:50176
	ds_read_b128 v[190:193], v153 offset:51200
	ds_read_b128 v[202:205], v153 offset:52224
	ds_read_b128 v[206:209], v153 offset:53248
	ds_read_b128 v[210:213], v153 offset:54272
	ds_read_b128 v[214:217], v153 offset:55296
	ds_read_b128 v[218:221], v153 offset:56320
	global_load_lds_dwordx4 v[194:195], off
	s_add_i32 m0, s38, 0x2000
	s_add_u32 s36, s36, 0x40080
	v_lshl_add_u64 v[194:195], v[198:199], 0, s[90:91]
	s_addc_u32 s37, s37, 0
	s_add_i32 s38, s86, s44
	global_load_lds_dwordx4 v[194:195], off
	v_lshl_add_u64 v[194:195], s[36:37], 0, v[134:135]
	s_mov_b32 m0, s38
	s_nop 0
	global_load_lds_dwordx4 v[194:195], off
	v_lshl_add_u64 v[194:195], s[36:37], 0, v[130:131]
	s_add_i32 m0, s38, 0x2000
	s_nop 0
	global_load_lds_dwordx4 v[194:195], off
	v_lshl_add_u64 v[194:195], s[34:35], 0, v[136:137]
	s_mov_b32 m0, s58
	s_nop 0
	global_load_lds_dwordx4 v[194:195], off
	v_lshl_add_u64 v[194:195], s[34:35], 0, v[132:133]
	s_mov_b32 m0, s59
	s_nop 0
	global_load_lds_dwordx4 v[194:195], off
	s_waitcnt vmcnt(8)
	s_waitcnt lgkmcnt(0)
	s_barrier
	s_setprio 1
	v_mfma_f32_16x16x32_bf16 v[62:65], v[148:151], v[182:185], v[62:65]
	v_mfma_f32_16x16x32_bf16 v[58:61], v[158:161], v[182:185], v[58:61]
	v_mfma_f32_16x16x32_bf16 v[46:49], v[148:151], v[190:193], v[46:49]
	v_mfma_f32_16x16x32_bf16 v[42:45], v[158:161], v[190:193], v[42:45]
	v_mfma_f32_16x16x32_bf16 v[30:33], v[148:151], v[206:209], v[30:33]
	v_mfma_f32_16x16x32_bf16 v[26:29], v[158:161], v[206:209], v[26:29]
	v_mfma_f32_16x16x32_bf16 v[14:17], v[148:151], v[214:217], v[14:17]
	v_mfma_f32_16x16x32_bf16 v[10:13], v[158:161], v[214:217], v[10:13]
	v_mfma_f32_16x16x32_bf16 v[62:65], v[154:157], v[186:189], v[62:65]
	v_mfma_f32_16x16x32_bf16 v[58:61], v[162:165], v[186:189], v[58:61]
	v_mfma_f32_16x16x32_bf16 v[46:49], v[154:157], v[202:205], v[46:49]
	v_mfma_f32_16x16x32_bf16 v[42:45], v[162:165], v[202:205], v[42:45]
	v_mfma_f32_16x16x32_bf16 v[30:33], v[154:157], v[210:213], v[30:33]
	v_mfma_f32_16x16x32_bf16 v[26:29], v[162:165], v[210:213], v[26:29]
	v_mfma_f32_16x16x32_bf16 v[14:17], v[154:157], v[218:221], v[14:17]
	v_mfma_f32_16x16x32_bf16 v[10:13], v[162:165], v[218:221], v[10:13]
	v_mfma_f32_16x16x32_bf16 v[54:57], v[166:169], v[182:185], v[54:57]
	v_mfma_f32_16x16x32_bf16 v[50:53], v[174:177], v[182:185], v[50:53]
	v_mfma_f32_16x16x32_bf16 v[38:41], v[166:169], v[190:193], v[38:41]
	v_mfma_f32_16x16x32_bf16 v[34:37], v[174:177], v[190:193], v[34:37]
	v_mfma_f32_16x16x32_bf16 v[22:25], v[166:169], v[206:209], v[22:25]
	v_mfma_f32_16x16x32_bf16 v[18:21], v[174:177], v[206:209], v[18:21]
	v_mfma_f32_16x16x32_bf16 v[6:9], v[166:169], v[214:217], v[6:9]
	v_mfma_f32_16x16x32_bf16 v[2:5], v[174:177], v[214:217], v[2:5]
	v_mfma_f32_16x16x32_bf16 v[54:57], v[170:173], v[186:189], v[54:57]
	v_mfma_f32_16x16x32_bf16 v[50:53], v[178:181], v[186:189], v[50:53]
	v_mfma_f32_16x16x32_bf16 v[38:41], v[170:173], v[202:205], v[38:41]
	v_mfma_f32_16x16x32_bf16 v[34:37], v[178:181], v[202:205], v[34:37]
	v_mfma_f32_16x16x32_bf16 v[22:25], v[170:173], v[210:213], v[22:25]
	v_mfma_f32_16x16x32_bf16 v[18:21], v[178:181], v[210:213], v[18:21]
	v_mfma_f32_16x16x32_bf16 v[6:9], v[170:173], v[218:221], v[6:9]
	v_mfma_f32_16x16x32_bf16 v[2:5], v[178:181], v[218:221], v[2:5]
	s_setprio 0
	s_barrier
	s_add_i32 s78, s78, 2
	s_add_u32 s30, s30, 0x100
	s_addc_u32 s31, s31, 0
	s_cmp_gt_u32 s78, 13
	s_cbranch_scc0 .LBB0_345
	s_and_b64 vcc, exec, s[16:17]
	s_cbranch_vccz .LBB0_348
	s_barrier

.LBB0_541:
	s_add_i32 s78, s78, 2
	s_cmp_gt_u32 s78, 7
	s_cselect_b32 vcc_lo, 0xffffec00, 0
	s_cselect_b32 vcc_hi, -1, 0
	s_cmp_gt_u32 s78, 5
	s_cselect_b32 s11, 0xffffec00, 0
	s_cselect_b32 s10, -1, 0
	s_add_u32 s11, s11, s36
	s_addc_u32 s10, s10, s37
	s_add_u32 s11, s34, s11
	s_addc_u32 s10, s35, s10
	s_add_u32 s11, s11, 0x100
	s_addc_u32 s10, s10, 0
	s_add_u32 s38, s86, s36
	s_addc_u32 s39, s87, s37
	s_cmp_gt_u32 s78, 4
	s_cselect_b32 s41, 0xffffec00, 0
	s_cselect_b32 s40, -1, 0
	s_add_u32 s41, s41, s36
	s_addc_u32 s40, s40, s37
	s_add_u32 s41, s34, s41
	s_addc_u32 s40, s35, s40
	s_add_u32 s4, s41, 0x180
	s_addc_u32 s5, s40, 0
	s_cmpk_eq_i32 s36, 0x700
	s_cselect_b32 s41, s29, s10
	s_cselect_b32 s40, s28, s11
	s_cselect_b32 s39, s73, s39
	s_cselect_b32 s38, s74, s38
	s_cselect_b32 s11, s76, s5
	s_cselect_b32 s10, s75, s4
	s_add_i32 s4, 0, 0x10000
	v_add_u32_e32 v0, s4, v244
	s_add_i32 s5, 0, 0x14000
	ds_read_b128 v[132:135], v0
	ds_read_b128 v[136:139], v0 offset:1024
	ds_read_b128 v[144:147], v0 offset:2048
	ds_read_b128 v[148:151], v0 offset:3072
	v_add_u32_e32 v0, s5, v244
	ds_read_b128 v[152:155], v0
	ds_read_b128 v[156:159], v0 offset:1024
	ds_read_b128 v[160:163], v0 offset:2048
	ds_read_b128 v[164:167], v0 offset:3072
	s_add_u32 vcc_lo, vcc_lo, s36
	s_addc_u32 vcc_hi, vcc_hi, s37
	v_lshl_add_u64 v[2:3], v[140:141], 0, vcc
	s_add_i32 m0, s55, 0xc000
	ds_read_b128 v[168:171], v246
	ds_read_b128 v[172:175], v246 offset:1024
	ds_read_b128 v[176:179], v246 offset:2048
	ds_read_b128 v[180:183], v246 offset:3072
	ds_read_b128 v[184:187], v246 offset:4096
	ds_read_b128 v[188:191], v246 offset:5120
	ds_read_b128 v[212:215], v246 offset:6144
	ds_read_b128 v[216:219], v246 offset:7168
	global_load_lds_dwordx4 v[2:3], off
	v_lshl_add_u64 v[2:3], v[142:143], 0, vcc
	s_add_i32 m0, s55, 0xe000
	s_nop 0
	global_load_lds_dwordx4 v[2:3], off
	s_waitcnt vmcnt(8)
	s_waitcnt lgkmcnt(0)
	s_barrier
	s_setprio 1
	v_mfma_f32_16x16x32_bf16 v[128:131], v[132:135], v[168:171], v[128:131]
	v_mfma_f32_16x16x32_bf16 v[124:127], v[144:147], v[168:171], v[124:127]
	v_mfma_f32_16x16x32_bf16 v[112:115], v[132:135], v[176:179], v[112:115]
	v_mfma_f32_16x16x32_bf16 v[108:111], v[144:147], v[176:179], v[108:111]
	v_mfma_f32_16x16x32_bf16 v[96:99], v[132:135], v[184:187], v[96:99]
	v_mfma_f32_16x16x32_bf16 v[92:95], v[144:147], v[184:187], v[92:95]
	v_mfma_f32_16x16x32_bf16 v[80:83], v[132:135], v[212:215], v[80:83]
	v_mfma_f32_16x16x32_bf16 v[76:79], v[144:147], v[212:215], v[76:79]
	v_mfma_f32_16x16x32_bf16 v[128:131], v[136:139], v[172:175], v[128:131]
	v_mfma_f32_16x16x32_bf16 v[124:127], v[148:151], v[172:175], v[124:127]
	v_mfma_f32_16x16x32_bf16 v[112:115], v[136:139], v[180:183], v[112:115]
	v_mfma_f32_16x16x32_bf16 v[108:111], v[148:151], v[180:183], v[108:111]
	v_mfma_f32_16x16x32_bf16 v[96:99], v[136:139], v[188:191], v[96:99]
	v_mfma_f32_16x16x32_bf16 v[92:95], v[148:151], v[188:191], v[92:95]
	v_mfma_f32_16x16x32_bf16 v[80:83], v[136:139], v[216:219], v[80:83]
	v_mfma_f32_16x16x32_bf16 v[76:79], v[148:151], v[216:219], v[76:79]
	v_mfma_f32_16x16x32_bf16 v[120:123], v[152:155], v[168:171], v[120:123]
	v_mfma_f32_16x16x32_bf16 v[116:119], v[160:163], v[168:171], v[116:119]
	v_mfma_f32_16x16x32_bf16 v[104:107], v[152:155], v[176:179], v[104:107]
	v_mfma_f32_16x16x32_bf16 v[100:103], v[160:163], v[176:179], v[100:103]
	v_mfma_f32_16x16x32_bf16 v[88:91], v[152:155], v[184:187], v[88:91]
	v_mfma_f32_16x16x32_bf16 v[84:87], v[160:163], v[184:187], v[84:87]
	v_mfma_f32_16x16x32_bf16 v[72:75], v[152:155], v[212:215], v[72:75]
	v_mfma_f32_16x16x32_bf16 v[68:71], v[160:163], v[212:215], v[68:71]
	v_mfma_f32_16x16x32_bf16 v[120:123], v[156:159], v[172:175], v[120:123]
	v_mfma_f32_16x16x32_bf16 v[116:119], v[164:167], v[172:175], v[116:119]
	v_mfma_f32_16x16x32_bf16 v[104:107], v[156:159], v[180:183], v[104:107]
	v_mfma_f32_16x16x32_bf16 v[100:103], v[164:167], v[180:183], v[100:103]
	v_mfma_f32_16x16x32_bf16 v[88:91], v[156:159], v[188:191], v[88:91]
	v_mfma_f32_16x16x32_bf16 v[84:87], v[164:167], v[188:191], v[84:87]
	v_mfma_f32_16x16x32_bf16 v[72:75], v[156:159], v[216:219], v[72:75]
	v_mfma_f32_16x16x32_bf16 v[68:71], v[164:167], v[216:219], v[68:71]
	s_setprio 0
	s_barrier
	s_add_i32 s4, s4, s51
	v_lshl_add_u64 v[194:195], s[38:39], 0, v[204:205]
	s_mov_b32 m0, s4
	ds_read_b128 v[168:171], v246 offset:16384
	ds_read_b128 v[172:175], v246 offset:17408
	ds_read_b128 v[176:179], v246 offset:18432
	ds_read_b128 v[180:183], v246 offset:19456
	ds_read_b128 v[184:187], v246 offset:20480
	ds_read_b128 v[188:191], v246 offset:21504
	ds_read_b128 v[212:215], v246 offset:22528
	ds_read_b128 v[216:219], v246 offset:23552
	global_load_lds_dwordx4 v[194:195], off
	s_add_i32 m0, s4, 0x2000
	s_add_u32 vcc_lo, s38, 0x40000
	v_lshl_add_u64 v[198:199], s[38:39], 0, v[192:193]
	s_addc_u32 vcc_hi, s39, 0
	s_add_i32 s4, s5, s51
	global_load_lds_dwordx4 v[198:199], off
	v_lshl_add_u64 v[2:3], vcc, 0, v[204:205]
	s_mov_b32 m0, s4
	s_nop 0
	global_load_lds_dwordx4 v[2:3], off
	v_lshl_add_u64 v[2:3], vcc, 0, v[192:193]
	s_add_i32 m0, s4, 0x2000
	s_nop 0
	global_load_lds_dwordx4 v[2:3], off
	v_lshl_add_u64 v[2:3], s[40:41], 0, v[206:207]
	s_mov_b32 m0, s55
	s_nop 0
	global_load_lds_dwordx4 v[2:3], off
	v_lshl_add_u64 v[2:3], s[40:41], 0, v[202:203]
	s_mov_b32 m0, s56
	s_nop 0
	global_load_lds_dwordx4 v[2:3], off
	s_waitcnt vmcnt(8)
	s_waitcnt lgkmcnt(0)
	s_barrier
	s_setprio 1
	v_mfma_f32_16x16x32_bf16 v[64:67], v[132:135], v[168:171], v[64:67]
	v_mfma_f32_16x16x32_bf16 v[60:63], v[144:147], v[168:171], v[60:63]
	v_mfma_f32_16x16x32_bf16 v[48:51], v[132:135], v[176:179], v[48:51]
	v_mfma_f32_16x16x32_bf16 v[44:47], v[144:147], v[176:179], v[44:47]
	v_mfma_f32_16x16x32_bf16 v[32:35], v[132:135], v[184:187], v[32:35]
	v_mfma_f32_16x16x32_bf16 v[28:31], v[144:147], v[184:187], v[28:31]
	v_mfma_f32_16x16x32_bf16 v[16:19], v[132:135], v[212:215], v[16:19]
	v_mfma_f32_16x16x32_bf16 v[12:15], v[144:147], v[212:215], v[12:15]
	v_mfma_f32_16x16x32_bf16 v[64:67], v[136:139], v[172:175], v[64:67]
	v_mfma_f32_16x16x32_bf16 v[60:63], v[148:151], v[172:175], v[60:63]
	v_mfma_f32_16x16x32_bf16 v[48:51], v[136:139], v[180:183], v[48:51]
	v_mfma_f32_16x16x32_bf16 v[44:47], v[148:151], v[180:183], v[44:47]
	v_mfma_f32_16x16x32_bf16 v[32:35], v[136:139], v[188:191], v[32:35]
	v_mfma_f32_16x16x32_bf16 v[28:31], v[148:151], v[188:191], v[28:31]
	v_mfma_f32_16x16x32_bf16 v[16:19], v[136:139], v[216:219], v[16:19]
	v_mfma_f32_16x16x32_bf16 v[12:15], v[148:151], v[216:219], v[12:15]
	v_mfma_f32_16x16x32_bf16 v[56:59], v[152:155], v[168:171], v[56:59]
	v_mfma_f32_16x16x32_bf16 v[52:55], v[160:163], v[168:171], v[52:55]
	v_mfma_f32_16x16x32_bf16 v[40:43], v[152:155], v[176:179], v[40:43]
	v_mfma_f32_16x16x32_bf16 v[36:39], v[160:163], v[176:179], v[36:39]
	v_mfma_f32_16x16x32_bf16 v[24:27], v[152:155], v[184:187], v[24:27]
	v_mfma_f32_16x16x32_bf16 v[20:23], v[160:163], v[184:187], v[20:23]
	v_mfma_f32_16x16x32_bf16 v[8:11], v[152:155], v[212:215], v[8:11]
	v_mfma_f32_16x16x32_bf16 v[2:5], v[160:163], v[212:215], v[4:7]
	v_mfma_f32_16x16x32_bf16 v[56:59], v[156:159], v[172:175], v[56:59]
	v_mfma_f32_16x16x32_bf16 v[52:55], v[164:167], v[172:175], v[52:55]
	v_mfma_f32_16x16x32_bf16 v[40:43], v[156:159], v[180:183], v[40:43]
	v_mfma_f32_16x16x32_bf16 v[36:39], v[164:167], v[180:183], v[36:39]
	v_mfma_f32_16x16x32_bf16 v[24:27], v[156:159], v[188:191], v[24:27]
	v_mfma_f32_16x16x32_bf16 v[20:23], v[164:167], v[188:191], v[20:23]
	v_mfma_f32_16x16x32_bf16 v[8:11], v[156:159], v[216:219], v[8:11]
	v_mfma_f32_16x16x32_bf16 v[2:5], v[164:167], v[216:219], v[2:5]
	s_setprio 0
	s_barrier
	s_add_i32 s4, 0, 0x18000
	v_add_u32_e32 v0, s4, v244
	s_add_i32 s5, 0, 0x1c000
	ds_read_b128 v[132:135], v0
	ds_read_b128 v[136:139], v0 offset:1024
	ds_read_b128 v[144:147], v0 offset:2048
	ds_read_b128 v[148:151], v0 offset:3072
	v_add_u32_e32 v0, s5, v244
	ds_read_b128 v[152:155], v0
	ds_read_b128 v[156:159], v0 offset:1024
	ds_read_b128 v[160:163], v0 offset:2048
	ds_read_b128 v[164:167], v0 offset:3072
	s_add_u32 s40, s40, 0xe0000
	s_addc_u32 s41, s41, 0
	s_mov_b32 m0, s57
	v_lshl_add_u64 v[6:7], s[40:41], 0, v[206:207]
	ds_read_b128 v[168:171], v246 offset:32768
	ds_read_b128 v[172:175], v246 offset:33792
	ds_read_b128 v[176:179], v246 offset:34816
	ds_read_b128 v[180:183], v246 offset:35840
	ds_read_b128 v[184:187], v246 offset:36864
	ds_read_b128 v[188:191], v246 offset:37888
	ds_read_b128 v[212:215], v246 offset:38912
	ds_read_b128 v[216:219], v246 offset:39936
	global_load_lds_dwordx4 v[6:7], off
	v_lshl_add_u64 v[6:7], s[40:41], 0, v[202:203]
	s_mov_b32 m0, s58
	s_nop 0
	global_load_lds_dwordx4 v[6:7], off
	s_waitcnt vmcnt(8)
	s_waitcnt lgkmcnt(0)
	s_barrier
	s_setprio 1
	v_mfma_f32_16x16x32_bf16 v[128:131], v[132:135], v[168:171], v[128:131]
	v_mfma_f32_16x16x32_bf16 v[124:127], v[144:147], v[168:171], v[124:127]
	v_mfma_f32_16x16x32_bf16 v[112:115], v[132:135], v[176:179], v[112:115]
	v_mfma_f32_16x16x32_bf16 v[108:111], v[144:147], v[176:179], v[108:111]
	v_mfma_f32_16x16x32_bf16 v[96:99], v[132:135], v[184:187], v[96:99]
	v_mfma_f32_16x16x32_bf16 v[92:95], v[144:147], v[184:187], v[92:95]
	v_mfma_f32_16x16x32_bf16 v[80:83], v[132:135], v[212:215], v[80:83]
	v_mfma_f32_16x16x32_bf16 v[76:79], v[144:147], v[212:215], v[76:79]
	v_mfma_f32_16x16x32_bf16 v[128:131], v[136:139], v[172:175], v[128:131]
	v_mfma_f32_16x16x32_bf16 v[124:127], v[148:151], v[172:175], v[124:127]
	v_mfma_f32_16x16x32_bf16 v[112:115], v[136:139], v[180:183], v[112:115]
	v_mfma_f32_16x16x32_bf16 v[108:111], v[148:151], v[180:183], v[108:111]
	v_mfma_f32_16x16x32_bf16 v[96:99], v[136:139], v[188:191], v[96:99]
	v_mfma_f32_16x16x32_bf16 v[92:95], v[148:151], v[188:191], v[92:95]
	v_mfma_f32_16x16x32_bf16 v[80:83], v[136:139], v[216:219], v[80:83]
	v_mfma_f32_16x16x32_bf16 v[76:79], v[148:151], v[216:219], v[76:79]
	v_mfma_f32_16x16x32_bf16 v[120:123], v[152:155], v[168:171], v[120:123]
	v_mfma_f32_16x16x32_bf16 v[116:119], v[160:163], v[168:171], v[116:119]
	v_mfma_f32_16x16x32_bf16 v[104:107], v[152:155], v[176:179], v[104:107]
	v_mfma_f32_16x16x32_bf16 v[100:103], v[160:163], v[176:179], v[100:103]
	v_mfma_f32_16x16x32_bf16 v[88:91], v[152:155], v[184:187], v[88:91]
	v_mfma_f32_16x16x32_bf16 v[84:87], v[160:163], v[184:187], v[84:87]
	v_mfma_f32_16x16x32_bf16 v[72:75], v[152:155], v[212:215], v[72:75]
	v_mfma_f32_16x16x32_bf16 v[68:71], v[160:163], v[212:215], v[68:71]
	v_mfma_f32_16x16x32_bf16 v[120:123], v[156:159], v[172:175], v[120:123]
	v_mfma_f32_16x16x32_bf16 v[116:119], v[164:167], v[172:175], v[116:119]
	v_mfma_f32_16x16x32_bf16 v[104:107], v[156:159], v[180:183], v[104:107]
	v_mfma_f32_16x16x32_bf16 v[100:103], v[164:167], v[180:183], v[100:103]
	v_mfma_f32_16x16x32_bf16 v[88:91], v[156:159], v[188:191], v[88:91]
	v_mfma_f32_16x16x32_bf16 v[84:87], v[164:167], v[188:191], v[84:87]
	v_mfma_f32_16x16x32_bf16 v[72:75], v[156:159], v[216:219], v[72:75]
	v_mfma_f32_16x16x32_bf16 v[68:71], v[164:167], v[216:219], v[68:71]
	s_setprio 0
	s_barrier
	s_add_i32 s4, s4, s51
	v_lshl_add_u64 v[6:7], v[194:195], 0, s[90:91]
	s_mov_b32 m0, s4
	ds_read_b128 v[168:171], v246 offset:49152
	ds_read_b128 v[172:175], v246 offset:50176
	ds_read_b128 v[176:179], v246 offset:51200
	ds_read_b128 v[180:183], v246 offset:52224
	ds_read_b128 v[184:187], v246 offset:53248
	ds_read_b128 v[188:191], v246 offset:54272
	ds_read_b128 v[212:215], v246 offset:55296
	ds_read_b128 v[216:219], v246 offset:56320
	global_load_lds_dwordx4 v[6:7], off
	s_add_i32 m0, s4, 0x2000
	s_add_u32 s38, s38, 0x40080
	v_lshl_add_u64 v[6:7], v[198:199], 0, s[90:91]
	s_addc_u32 s39, s39, 0
	s_add_i32 s4, s5, s51
	global_load_lds_dwordx4 v[6:7], off
	v_lshl_add_u64 v[6:7], s[38:39], 0, v[204:205]
	s_mov_b32 m0, s4
	s_nop 0
	global_load_lds_dwordx4 v[6:7], off
	v_lshl_add_u64 v[6:7], s[38:39], 0, v[192:193]
	s_add_i32 m0, s4, 0x2000
	s_nop 0
	global_load_lds_dwordx4 v[6:7], off
	v_lshl_add_u64 v[6:7], s[10:11], 0, v[206:207]
	s_mov_b32 m0, s68
	s_nop 0
	global_load_lds_dwordx4 v[6:7], off
	v_lshl_add_u64 v[6:7], s[10:11], 0, v[202:203]
	s_mov_b32 m0, s69
	s_nop 0
	global_load_lds_dwordx4 v[6:7], off
	s_waitcnt vmcnt(8)
	s_waitcnt lgkmcnt(0)
	s_barrier
	s_setprio 1
	v_mfma_f32_16x16x32_bf16 v[64:67], v[132:135], v[168:171], v[64:67]
	v_mfma_f32_16x16x32_bf16 v[60:63], v[144:147], v[168:171], v[60:63]
	v_mfma_f32_16x16x32_bf16 v[48:51], v[132:135], v[176:179], v[48:51]
	v_mfma_f32_16x16x32_bf16 v[44:47], v[144:147], v[176:179], v[44:47]
	v_mfma_f32_16x16x32_bf16 v[32:35], v[132:135], v[184:187], v[32:35]
	v_mfma_f32_16x16x32_bf16 v[28:31], v[144:147], v[184:187], v[28:31]
	v_mfma_f32_16x16x32_bf16 v[16:19], v[132:135], v[212:215], v[16:19]
	v_mfma_f32_16x16x32_bf16 v[12:15], v[144:147], v[212:215], v[12:15]
	v_mfma_f32_16x16x32_bf16 v[64:67], v[136:139], v[172:175], v[64:67]
	v_mfma_f32_16x16x32_bf16 v[60:63], v[148:151], v[172:175], v[60:63]
	v_mfma_f32_16x16x32_bf16 v[48:51], v[136:139], v[180:183], v[48:51]
	v_mfma_f32_16x16x32_bf16 v[44:47], v[148:151], v[180:183], v[44:47]
	v_mfma_f32_16x16x32_bf16 v[32:35], v[136:139], v[188:191], v[32:35]
	v_mfma_f32_16x16x32_bf16 v[28:31], v[148:151], v[188:191], v[28:31]
	v_mfma_f32_16x16x32_bf16 v[16:19], v[136:139], v[216:219], v[16:19]
	v_mfma_f32_16x16x32_bf16 v[12:15], v[148:151], v[216:219], v[12:15]
	v_mfma_f32_16x16x32_bf16 v[56:59], v[152:155], v[168:171], v[56:59]
	v_mfma_f32_16x16x32_bf16 v[52:55], v[160:163], v[168:171], v[52:55]
	v_mfma_f32_16x16x32_bf16 v[40:43], v[152:155], v[176:179], v[40:43]
	v_mfma_f32_16x16x32_bf16 v[36:39], v[160:163], v[176:179], v[36:39]
	v_mfma_f32_16x16x32_bf16 v[24:27], v[152:155], v[184:187], v[24:27]
	v_mfma_f32_16x16x32_bf16 v[20:23], v[160:163], v[184:187], v[20:23]
	v_mfma_f32_16x16x32_bf16 v[6:9], v[152:155], v[212:215], v[8:11]
	v_mfma_f32_16x16x32_bf16 v[2:5], v[160:163], v[212:215], v[2:5]
	v_mfma_f32_16x16x32_bf16 v[56:59], v[156:159], v[172:175], v[56:59]
	v_mfma_f32_16x16x32_bf16 v[52:55], v[164:167], v[172:175], v[52:55]
	v_mfma_f32_16x16x32_bf16 v[40:43], v[156:159], v[180:183], v[40:43]
	v_mfma_f32_16x16x32_bf16 v[36:39], v[164:167], v[180:183], v[36:39]
	v_mfma_f32_16x16x32_bf16 v[24:27], v[156:159], v[188:191], v[24:27]
	v_mfma_f32_16x16x32_bf16 v[20:23], v[164:167], v[188:191], v[20:23]
	v_mfma_f32_16x16x32_bf16 v[8:11], v[156:159], v[216:219], v[6:9]
	v_mfma_f32_16x16x32_bf16 v[4:7], v[164:167], v[216:219], v[2:5]
	s_setprio 0
	s_barrier
	s_add_u32 s36, s36, 0x100
	s_addc_u32 s37, s37, 0
	s_cmp_gt_u32 s78, 13
	s_cbranch_scc1 .LBB0_544

.LBB0_585:
	s_add_i32 s78, s78, 2
	s_cmp_gt_u32 s78, 7
	s_cselect_b32 s85, 0xffffec00, 0
	s_cselect_b32 s87, -1, 0
	s_cmp_gt_u32 s78, 5
	s_cselect_b32 s35, 0xffffec00, 0
	s_cselect_b32 s34, -1, 0
	s_add_u32 s35, s35, s12
	s_addc_u32 s34, s34, s13
	s_add_u32 s35, s30, s35
	s_addc_u32 s34, s31, s34
	s_add_u32 s35, s35, 0x100
	s_addc_u32 s34, s34, 0
	s_add_u32 s36, s75, s12
	s_addc_u32 s37, s76, s13
	s_cmp_gt_u32 s78, 4
	s_cselect_b32 s39, 0xffffec00, 0
	s_cselect_b32 s38, -1, 0
	s_add_u32 s39, s39, s12
	s_addc_u32 s38, s38, s13
	s_add_u32 s39, s30, s39
	s_addc_u32 s38, s31, s38
	s_add_u32 s86, s39, 0x180
	s_addc_u32 vcc_lo, s38, 0
	s_cmpk_eq_i32 s12, 0x700
	s_cselect_b32 s39, s27, s34
	s_cselect_b32 s38, s26, s35
	s_cselect_b32 s37, s25, s37
	s_cselect_b32 s36, s72, s36
	s_cselect_b32 s35, s74, vcc_lo
	s_cselect_b32 s34, s73, s86
	s_add_i32 vcc_lo, 0, 0x10000
	v_add_u32_e32 v0, vcc_lo, v243
	s_add_i32 vcc_hi, 0, 0x14000
	ds_read_b128 v[128:131], v0
	ds_read_b128 v[132:135], v0 offset:1024
	ds_read_b128 v[136:139], v0 offset:2048
	ds_read_b128 v[140:143], v0 offset:3072
	v_add_u32_e32 v0, vcc_hi, v243
	ds_read_b128 v[152:155], v0
	ds_read_b128 v[156:159], v0 offset:1024
	ds_read_b128 v[160:163], v0 offset:2048
	ds_read_b128 v[164:167], v0 offset:3072
	s_add_u32 s86, s85, s12
	s_addc_u32 s87, s87, s13
	v_lshl_add_u64 v[2:3], v[124:125], 0, s[86:87]
	s_add_i32 m0, s41, 0xc000
	ds_read_b128 v[168:171], v245
	ds_read_b128 v[172:175], v245 offset:1024
	ds_read_b128 v[176:179], v245 offset:2048
	ds_read_b128 v[180:183], v245 offset:3072
	ds_read_b128 v[184:187], v245 offset:4096
	ds_read_b128 v[188:191], v245 offset:5120
	ds_read_b128 v[212:215], v245 offset:6144
	ds_read_b128 v[216:219], v245 offset:7168
	global_load_lds_dwordx4 v[2:3], off
	v_lshl_add_u64 v[2:3], v[126:127], 0, s[86:87]
	s_add_i32 m0, s41, 0xe000
	s_nop 0
	global_load_lds_dwordx4 v[2:3], off
	s_waitcnt vmcnt(8)
	s_waitcnt lgkmcnt(0)
	s_barrier
	s_setprio 1
	v_mfma_f32_16x16x32_bf16 v[148:151], v[128:131], v[168:171], v[148:151]
	v_mfma_f32_16x16x32_bf16 v[144:147], v[136:139], v[168:171], v[144:147]
	v_mfma_f32_16x16x32_bf16 v[112:115], v[128:131], v[176:179], v[112:115]
	v_mfma_f32_16x16x32_bf16 v[108:111], v[136:139], v[176:179], v[108:111]
	v_mfma_f32_16x16x32_bf16 v[96:99], v[128:131], v[184:187], v[96:99]
	v_mfma_f32_16x16x32_bf16 v[92:95], v[136:139], v[184:187], v[92:95]
	v_mfma_f32_16x16x32_bf16 v[80:83], v[128:131], v[212:215], v[80:83]
	v_mfma_f32_16x16x32_bf16 v[76:79], v[136:139], v[212:215], v[76:79]
	v_mfma_f32_16x16x32_bf16 v[148:151], v[132:135], v[172:175], v[148:151]
	v_mfma_f32_16x16x32_bf16 v[144:147], v[140:143], v[172:175], v[144:147]
	v_mfma_f32_16x16x32_bf16 v[112:115], v[132:135], v[180:183], v[112:115]
	v_mfma_f32_16x16x32_bf16 v[108:111], v[140:143], v[180:183], v[108:111]
	v_mfma_f32_16x16x32_bf16 v[96:99], v[132:135], v[188:191], v[96:99]
	v_mfma_f32_16x16x32_bf16 v[92:95], v[140:143], v[188:191], v[92:95]
	v_mfma_f32_16x16x32_bf16 v[80:83], v[132:135], v[216:219], v[80:83]
	v_mfma_f32_16x16x32_bf16 v[76:79], v[140:143], v[216:219], v[76:79]
	v_mfma_f32_16x16x32_bf16 v[120:123], v[152:155], v[168:171], v[120:123]
	v_mfma_f32_16x16x32_bf16 v[116:119], v[160:163], v[168:171], v[116:119]
	v_mfma_f32_16x16x32_bf16 v[104:107], v[152:155], v[176:179], v[104:107]
	v_mfma_f32_16x16x32_bf16 v[100:103], v[160:163], v[176:179], v[100:103]
	v_mfma_f32_16x16x32_bf16 v[88:91], v[152:155], v[184:187], v[88:91]
	v_mfma_f32_16x16x32_bf16 v[84:87], v[160:163], v[184:187], v[84:87]
	v_mfma_f32_16x16x32_bf16 v[72:75], v[152:155], v[212:215], v[72:75]
	v_mfma_f32_16x16x32_bf16 v[68:71], v[160:163], v[212:215], v[68:71]
	v_mfma_f32_16x16x32_bf16 v[120:123], v[156:159], v[172:175], v[120:123]
	v_mfma_f32_16x16x32_bf16 v[116:119], v[164:167], v[172:175], v[116:119]
	v_mfma_f32_16x16x32_bf16 v[104:107], v[156:159], v[180:183], v[104:107]
	v_mfma_f32_16x16x32_bf16 v[100:103], v[164:167], v[180:183], v[100:103]
	v_mfma_f32_16x16x32_bf16 v[88:91], v[156:159], v[188:191], v[88:91]
	v_mfma_f32_16x16x32_bf16 v[84:87], v[164:167], v[188:191], v[84:87]
	v_mfma_f32_16x16x32_bf16 v[72:75], v[156:159], v[216:219], v[72:75]
	v_mfma_f32_16x16x32_bf16 v[68:71], v[164:167], v[216:219], v[68:71]
	s_setprio 0
	s_barrier
	s_add_i32 s85, vcc_lo, s40
	v_lshl_add_u64 v[194:195], s[36:37], 0, v[204:205]
	s_mov_b32 m0, s85
	ds_read_b128 v[168:171], v245 offset:16384
	ds_read_b128 v[172:175], v245 offset:17408
	ds_read_b128 v[176:179], v245 offset:18432
	ds_read_b128 v[180:183], v245 offset:19456
	ds_read_b128 v[184:187], v245 offset:20480
	ds_read_b128 v[188:191], v245 offset:21504
	ds_read_b128 v[212:215], v245 offset:22528
	ds_read_b128 v[216:219], v245 offset:23552
	global_load_lds_dwordx4 v[194:195], off
	s_add_i32 m0, s85, 0x2000
	s_add_u32 s86, s36, 0x40000
	v_lshl_add_u64 v[198:199], s[36:37], 0, v[192:193]
	s_addc_u32 s87, s37, 0
	s_add_i32 s85, vcc_hi, s40
	global_load_lds_dwordx4 v[198:199], off
	v_lshl_add_u64 v[2:3], s[86:87], 0, v[204:205]
	s_mov_b32 m0, s85
	s_nop 0
	global_load_lds_dwordx4 v[2:3], off
	v_lshl_add_u64 v[2:3], s[86:87], 0, v[192:193]
	s_add_i32 m0, s85, 0x2000
	s_nop 0
	global_load_lds_dwordx4 v[2:3], off
	v_lshl_add_u64 v[2:3], s[38:39], 0, v[206:207]
	s_mov_b32 m0, s41
	s_nop 0
	global_load_lds_dwordx4 v[2:3], off
	v_lshl_add_u64 v[2:3], s[38:39], 0, v[202:203]
	s_mov_b32 m0, s51
	s_nop 0
	global_load_lds_dwordx4 v[2:3], off
	s_waitcnt vmcnt(8)
	s_waitcnt lgkmcnt(0)
	s_barrier
	s_setprio 1
	v_mfma_f32_16x16x32_bf16 v[64:67], v[128:131], v[168:171], v[64:67]
	v_mfma_f32_16x16x32_bf16 v[60:63], v[136:139], v[168:171], v[60:63]
	v_mfma_f32_16x16x32_bf16 v[48:51], v[128:131], v[176:179], v[48:51]
	v_mfma_f32_16x16x32_bf16 v[44:47], v[136:139], v[176:179], v[44:47]
	v_mfma_f32_16x16x32_bf16 v[32:35], v[128:131], v[184:187], v[32:35]
	v_mfma_f32_16x16x32_bf16 v[28:31], v[136:139], v[184:187], v[28:31]
	v_mfma_f32_16x16x32_bf16 v[16:19], v[128:131], v[212:215], v[16:19]
	v_mfma_f32_16x16x32_bf16 v[12:15], v[136:139], v[212:215], v[12:15]
	v_mfma_f32_16x16x32_bf16 v[64:67], v[132:135], v[172:175], v[64:67]
	v_mfma_f32_16x16x32_bf16 v[60:63], v[140:143], v[172:175], v[60:63]
	v_mfma_f32_16x16x32_bf16 v[48:51], v[132:135], v[180:183], v[48:51]
	v_mfma_f32_16x16x32_bf16 v[44:47], v[140:143], v[180:183], v[44:47]
	v_mfma_f32_16x16x32_bf16 v[32:35], v[132:135], v[188:191], v[32:35]
	v_mfma_f32_16x16x32_bf16 v[28:31], v[140:143], v[188:191], v[28:31]
	v_mfma_f32_16x16x32_bf16 v[16:19], v[132:135], v[216:219], v[16:19]
	v_mfma_f32_16x16x32_bf16 v[12:15], v[140:143], v[216:219], v[12:15]
	v_mfma_f32_16x16x32_bf16 v[56:59], v[152:155], v[168:171], v[56:59]
	v_mfma_f32_16x16x32_bf16 v[52:55], v[160:163], v[168:171], v[52:55]
	v_mfma_f32_16x16x32_bf16 v[40:43], v[152:155], v[176:179], v[40:43]
	v_mfma_f32_16x16x32_bf16 v[36:39], v[160:163], v[176:179], v[36:39]
	v_mfma_f32_16x16x32_bf16 v[24:27], v[152:155], v[184:187], v[24:27]
	v_mfma_f32_16x16x32_bf16 v[20:23], v[160:163], v[184:187], v[20:23]
	v_mfma_f32_16x16x32_bf16 v[8:11], v[152:155], v[212:215], v[8:11]
	v_mfma_f32_16x16x32_bf16 v[2:5], v[160:163], v[212:215], v[4:7]
	v_mfma_f32_16x16x32_bf16 v[56:59], v[156:159], v[172:175], v[56:59]
	v_mfma_f32_16x16x32_bf16 v[52:55], v[164:167], v[172:175], v[52:55]
	v_mfma_f32_16x16x32_bf16 v[40:43], v[156:159], v[180:183], v[40:43]
	v_mfma_f32_16x16x32_bf16 v[36:39], v[164:167], v[180:183], v[36:39]
	v_mfma_f32_16x16x32_bf16 v[24:27], v[156:159], v[188:191], v[24:27]
	v_mfma_f32_16x16x32_bf16 v[20:23], v[164:167], v[188:191], v[20:23]
	v_mfma_f32_16x16x32_bf16 v[8:11], v[156:159], v[216:219], v[8:11]
	v_mfma_f32_16x16x32_bf16 v[2:5], v[164:167], v[216:219], v[2:5]
	s_setprio 0
	s_barrier
	s_add_i32 s85, 0, 0x18000
	v_add_u32_e32 v0, s85, v243
	s_add_i32 s86, 0, 0x1c000
	ds_read_b128 v[128:131], v0
	ds_read_b128 v[132:135], v0 offset:1024
	ds_read_b128 v[136:139], v0 offset:2048
	ds_read_b128 v[140:143], v0 offset:3072
	v_add_u32_e32 v0, s86, v243
	ds_read_b128 v[152:155], v0
	ds_read_b128 v[156:159], v0 offset:1024
	ds_read_b128 v[160:163], v0 offset:2048
	ds_read_b128 v[164:167], v0 offset:3072
	s_add_u32 s38, s38, 0xe0000
	s_addc_u32 s39, s39, 0
	s_mov_b32 m0, s55
	v_lshl_add_u64 v[6:7], s[38:39], 0, v[206:207]
	ds_read_b128 v[168:171], v245 offset:32768
	ds_read_b128 v[172:175], v245 offset:33792
	ds_read_b128 v[176:179], v245 offset:34816
	ds_read_b128 v[180:183], v245 offset:35840
	ds_read_b128 v[184:187], v245 offset:36864
	ds_read_b128 v[188:191], v245 offset:37888
	ds_read_b128 v[212:215], v245 offset:38912
	ds_read_b128 v[216:219], v245 offset:39936
	global_load_lds_dwordx4 v[6:7], off
	v_lshl_add_u64 v[6:7], s[38:39], 0, v[202:203]
	s_mov_b32 m0, s56
	s_nop 0
	global_load_lds_dwordx4 v[6:7], off
	s_waitcnt vmcnt(8)
	s_waitcnt lgkmcnt(0)
	s_barrier
	s_setprio 1
	v_mfma_f32_16x16x32_bf16 v[148:151], v[128:131], v[168:171], v[148:151]
	v_mfma_f32_16x16x32_bf16 v[144:147], v[136:139], v[168:171], v[144:147]
	v_mfma_f32_16x16x32_bf16 v[112:115], v[128:131], v[176:179], v[112:115]
	v_mfma_f32_16x16x32_bf16 v[108:111], v[136:139], v[176:179], v[108:111]
	v_mfma_f32_16x16x32_bf16 v[96:99], v[128:131], v[184:187], v[96:99]
	v_mfma_f32_16x16x32_bf16 v[92:95], v[136:139], v[184:187], v[92:95]
	v_mfma_f32_16x16x32_bf16 v[80:83], v[128:131], v[212:215], v[80:83]
	v_mfma_f32_16x16x32_bf16 v[76:79], v[136:139], v[212:215], v[76:79]
	v_mfma_f32_16x16x32_bf16 v[148:151], v[132:135], v[172:175], v[148:151]
	v_mfma_f32_16x16x32_bf16 v[144:147], v[140:143], v[172:175], v[144:147]
	v_mfma_f32_16x16x32_bf16 v[112:115], v[132:135], v[180:183], v[112:115]
	v_mfma_f32_16x16x32_bf16 v[108:111], v[140:143], v[180:183], v[108:111]
	v_mfma_f32_16x16x32_bf16 v[96:99], v[132:135], v[188:191], v[96:99]
	v_mfma_f32_16x16x32_bf16 v[92:95], v[140:143], v[188:191], v[92:95]
	v_mfma_f32_16x16x32_bf16 v[80:83], v[132:135], v[216:219], v[80:83]
	v_mfma_f32_16x16x32_bf16 v[76:79], v[140:143], v[216:219], v[76:79]
	v_mfma_f32_16x16x32_bf16 v[120:123], v[152:155], v[168:171], v[120:123]
	v_mfma_f32_16x16x32_bf16 v[116:119], v[160:163], v[168:171], v[116:119]
	v_mfma_f32_16x16x32_bf16 v[104:107], v[152:155], v[176:179], v[104:107]
	v_mfma_f32_16x16x32_bf16 v[100:103], v[160:163], v[176:179], v[100:103]
	v_mfma_f32_16x16x32_bf16 v[88:91], v[152:155], v[184:187], v[88:91]
	v_mfma_f32_16x16x32_bf16 v[84:87], v[160:163], v[184:187], v[84:87]
	v_mfma_f32_16x16x32_bf16 v[72:75], v[152:155], v[212:215], v[72:75]
	v_mfma_f32_16x16x32_bf16 v[68:71], v[160:163], v[212:215], v[68:71]
	v_mfma_f32_16x16x32_bf16 v[120:123], v[156:159], v[172:175], v[120:123]
	v_mfma_f32_16x16x32_bf16 v[116:119], v[164:167], v[172:175], v[116:119]
	v_mfma_f32_16x16x32_bf16 v[104:107], v[156:159], v[180:183], v[104:107]
	v_mfma_f32_16x16x32_bf16 v[100:103], v[164:167], v[180:183], v[100:103]
	v_mfma_f32_16x16x32_bf16 v[88:91], v[156:159], v[188:191], v[88:91]
	v_mfma_f32_16x16x32_bf16 v[84:87], v[164:167], v[188:191], v[84:87]
	v_mfma_f32_16x16x32_bf16 v[72:75], v[156:159], v[216:219], v[72:75]
	v_mfma_f32_16x16x32_bf16 v[68:71], v[164:167], v[216:219], v[68:71]
	s_setprio 0
	s_barrier
	s_add_i32 s38, s85, s40
	v_lshl_add_u64 v[6:7], v[194:195], 0, s[90:91]
	s_mov_b32 m0, s38
	ds_read_b128 v[168:171], v245 offset:49152
	ds_read_b128 v[172:175], v245 offset:50176
	ds_read_b128 v[176:179], v245 offset:51200
	ds_read_b128 v[180:183], v245 offset:52224
	ds_read_b128 v[184:187], v245 offset:53248
	ds_read_b128 v[188:191], v245 offset:54272
	ds_read_b128 v[212:215], v245 offset:55296
	ds_read_b128 v[216:219], v245 offset:56320
	global_load_lds_dwordx4 v[6:7], off
	s_add_i32 m0, s38, 0x2000
	s_add_u32 s36, s36, 0x40080
	v_lshl_add_u64 v[6:7], v[198:199], 0, s[90:91]
	s_addc_u32 s37, s37, 0
	s_add_i32 s38, s86, s40
	global_load_lds_dwordx4 v[6:7], off
	v_lshl_add_u64 v[6:7], s[36:37], 0, v[204:205]
	s_mov_b32 m0, s38
	s_nop 0
	global_load_lds_dwordx4 v[6:7], off
	v_lshl_add_u64 v[6:7], s[36:37], 0, v[192:193]
	s_add_i32 m0, s38, 0x2000
	s_nop 0
	global_load_lds_dwordx4 v[6:7], off
	v_lshl_add_u64 v[6:7], s[34:35], 0, v[206:207]
	s_mov_b32 m0, s57
	s_nop 0
	global_load_lds_dwordx4 v[6:7], off
	v_lshl_add_u64 v[6:7], s[34:35], 0, v[202:203]
	s_mov_b32 m0, s58
	s_nop 0
	global_load_lds_dwordx4 v[6:7], off
	s_waitcnt vmcnt(8)
	s_waitcnt lgkmcnt(0)
	s_barrier
	s_setprio 1
	v_mfma_f32_16x16x32_bf16 v[64:67], v[128:131], v[168:171], v[64:67]
	v_mfma_f32_16x16x32_bf16 v[60:63], v[136:139], v[168:171], v[60:63]
	v_mfma_f32_16x16x32_bf16 v[48:51], v[128:131], v[176:179], v[48:51]
	v_mfma_f32_16x16x32_bf16 v[44:47], v[136:139], v[176:179], v[44:47]
	v_mfma_f32_16x16x32_bf16 v[32:35], v[128:131], v[184:187], v[32:35]
	v_mfma_f32_16x16x32_bf16 v[28:31], v[136:139], v[184:187], v[28:31]
	v_mfma_f32_16x16x32_bf16 v[16:19], v[128:131], v[212:215], v[16:19]
	v_mfma_f32_16x16x32_bf16 v[12:15], v[136:139], v[212:215], v[12:15]
	v_mfma_f32_16x16x32_bf16 v[64:67], v[132:135], v[172:175], v[64:67]
	v_mfma_f32_16x16x32_bf16 v[60:63], v[140:143], v[172:175], v[60:63]
	v_mfma_f32_16x16x32_bf16 v[48:51], v[132:135], v[180:183], v[48:51]
	v_mfma_f32_16x16x32_bf16 v[44:47], v[140:143], v[180:183], v[44:47]
	v_mfma_f32_16x16x32_bf16 v[32:35], v[132:135], v[188:191], v[32:35]
	v_mfma_f32_16x16x32_bf16 v[28:31], v[140:143], v[188:191], v[28:31]
	v_mfma_f32_16x16x32_bf16 v[16:19], v[132:135], v[216:219], v[16:19]
	v_mfma_f32_16x16x32_bf16 v[12:15], v[140:143], v[216:219], v[12:15]
	v_mfma_f32_16x16x32_bf16 v[56:59], v[152:155], v[168:171], v[56:59]
	v_mfma_f32_16x16x32_bf16 v[52:55], v[160:163], v[168:171], v[52:55]
	v_mfma_f32_16x16x32_bf16 v[40:43], v[152:155], v[176:179], v[40:43]
	v_mfma_f32_16x16x32_bf16 v[36:39], v[160:163], v[176:179], v[36:39]
	v_mfma_f32_16x16x32_bf16 v[24:27], v[152:155], v[184:187], v[24:27]
	v_mfma_f32_16x16x32_bf16 v[20:23], v[160:163], v[184:187], v[20:23]
	v_mfma_f32_16x16x32_bf16 v[6:9], v[152:155], v[212:215], v[8:11]
	v_mfma_f32_16x16x32_bf16 v[2:5], v[160:163], v[212:215], v[2:5]
	v_mfma_f32_16x16x32_bf16 v[56:59], v[156:159], v[172:175], v[56:59]
	v_mfma_f32_16x16x32_bf16 v[52:55], v[164:167], v[172:175], v[52:55]
	v_mfma_f32_16x16x32_bf16 v[40:43], v[156:159], v[180:183], v[40:43]
	v_mfma_f32_16x16x32_bf16 v[36:39], v[164:167], v[180:183], v[36:39]
	v_mfma_f32_16x16x32_bf16 v[24:27], v[156:159], v[188:191], v[24:27]
	v_mfma_f32_16x16x32_bf16 v[20:23], v[164:167], v[188:191], v[20:23]
	v_mfma_f32_16x16x32_bf16 v[8:11], v[156:159], v[216:219], v[6:9]
	v_mfma_f32_16x16x32_bf16 v[4:7], v[164:167], v[216:219], v[2:5]
	s_setprio 0
	s_barrier
	s_add_u32 s12, s12, 0x100
	s_addc_u32 s13, s13, 0
	s_cmp_gt_u32 s78, 13
	s_cbranch_scc1 .LBB0_588

.LBB0_675:
	s_add_u32 s4, s30, s34
	s_addc_u32 s5, s31, s35
	s_add_u32 s40, s4, 0x100
	s_addc_u32 s41, s5, 0
	s_add_u32 s38, s78, s34
	s_addc_u32 s39, s85, s35
	s_add_u32 s4, s4, 0x180
	s_addc_u32 s5, s5, 0
	s_add_i32 s87, 0, 0x10000
	s_add_i32 s65, 0, 0x14000
	v_add_u32_e32 v0, s87, v148
	ds_read_b128 v[150:153], v0
	ds_read_b128 v[154:157], v0 offset:1024
	ds_read_b128 v[158:161], v0 offset:2048
	ds_read_b128 v[162:165], v0 offset:3072
	v_add_u32_e32 v0, s65, v148
	ds_read_b128 v[166:169], v0
	ds_read_b128 v[170:173], v0 offset:1024
	ds_read_b128 v[174:177], v0 offset:2048
	ds_read_b128 v[178:181], v0 offset:3072
	s_cmpk_eq_i32 s34, 0x700
	s_cselect_b32 s37, s76, s5
	s_cselect_b32 s36, s75, s4
	s_cselect_b32 s39, s23, s39
	s_cselect_b32 s38, s74, s38
	s_cselect_b32 s41, s25, s41
	s_cselect_b32 s40, s73, s40
	v_lshl_add_u64 v[194:195], v[144:145], 0, s[34:35]
	s_add_i32 m0, s55, 0xc000
	ds_read_b128 v[182:185], v149
	ds_read_b128 v[186:189], v149 offset:1024
	ds_read_b128 v[190:193], v149 offset:2048
	ds_read_b128 v[202:205], v149 offset:3072
	ds_read_b128 v[206:209], v149 offset:4096
	ds_read_b128 v[210:213], v149 offset:5120
	ds_read_b128 v[214:217], v149 offset:6144
	ds_read_b128 v[218:221], v149 offset:7168
	global_load_lds_dwordx4 v[194:195], off
	v_lshl_add_u64 v[194:195], v[146:147], 0, s[34:35]
	s_add_i32 m0, s55, 0xe000
	s_nop 0
	global_load_lds_dwordx4 v[194:195], off
	s_waitcnt vmcnt(8)
	s_waitcnt lgkmcnt(0)
	s_barrier
	s_setprio 1
	v_mfma_f32_16x16x32_bf16 v[126:129], v[150:153], v[182:185], v[126:129]
	v_mfma_f32_16x16x32_bf16 v[122:125], v[158:161], v[182:185], v[122:125]
	v_mfma_f32_16x16x32_bf16 v[110:113], v[150:153], v[190:193], v[110:113]
	v_mfma_f32_16x16x32_bf16 v[106:109], v[158:161], v[190:193], v[106:109]
	v_mfma_f32_16x16x32_bf16 v[94:97], v[150:153], v[206:209], v[94:97]
	v_mfma_f32_16x16x32_bf16 v[90:93], v[158:161], v[206:209], v[90:93]
	v_mfma_f32_16x16x32_bf16 v[78:81], v[150:153], v[214:217], v[78:81]
	v_mfma_f32_16x16x32_bf16 v[74:77], v[158:161], v[214:217], v[74:77]
	v_mfma_f32_16x16x32_bf16 v[126:129], v[154:157], v[186:189], v[126:129]
	v_mfma_f32_16x16x32_bf16 v[122:125], v[162:165], v[186:189], v[122:125]
	v_mfma_f32_16x16x32_bf16 v[110:113], v[154:157], v[202:205], v[110:113]
	v_mfma_f32_16x16x32_bf16 v[106:109], v[162:165], v[202:205], v[106:109]
	v_mfma_f32_16x16x32_bf16 v[94:97], v[154:157], v[210:213], v[94:97]
	v_mfma_f32_16x16x32_bf16 v[90:93], v[162:165], v[210:213], v[90:93]
	v_mfma_f32_16x16x32_bf16 v[78:81], v[154:157], v[218:221], v[78:81]
	v_mfma_f32_16x16x32_bf16 v[74:77], v[162:165], v[218:221], v[74:77]
	v_mfma_f32_16x16x32_bf16 v[118:121], v[166:169], v[182:185], v[118:121]
	v_mfma_f32_16x16x32_bf16 v[114:117], v[174:177], v[182:185], v[114:117]
	v_mfma_f32_16x16x32_bf16 v[102:105], v[166:169], v[190:193], v[102:105]
	v_mfma_f32_16x16x32_bf16 v[98:101], v[174:177], v[190:193], v[98:101]
	v_mfma_f32_16x16x32_bf16 v[86:89], v[166:169], v[206:209], v[86:89]
	v_mfma_f32_16x16x32_bf16 v[82:85], v[174:177], v[206:209], v[82:85]
	v_mfma_f32_16x16x32_bf16 v[70:73], v[166:169], v[214:217], v[70:73]
	v_mfma_f32_16x16x32_bf16 v[66:69], v[174:177], v[214:217], v[66:69]
	v_mfma_f32_16x16x32_bf16 v[118:121], v[170:173], v[186:189], v[118:121]
	v_mfma_f32_16x16x32_bf16 v[114:117], v[178:181], v[186:189], v[114:117]
	v_mfma_f32_16x16x32_bf16 v[102:105], v[170:173], v[202:205], v[102:105]
	v_mfma_f32_16x16x32_bf16 v[98:101], v[178:181], v[202:205], v[98:101]
	v_mfma_f32_16x16x32_bf16 v[86:89], v[170:173], v[210:213], v[86:89]
	v_mfma_f32_16x16x32_bf16 v[82:85], v[178:181], v[210:213], v[82:85]
	v_mfma_f32_16x16x32_bf16 v[70:73], v[170:173], v[218:221], v[70:73]
	v_mfma_f32_16x16x32_bf16 v[66:69], v[178:181], v[218:221], v[66:69]
	s_setprio 0
	s_barrier
	s_add_i32 s4, s87, s51
	v_lshl_add_u64 v[194:195], s[38:39], 0, v[134:135]
	s_mov_b32 m0, s4
	ds_read_b128 v[182:185], v149 offset:16384
	ds_read_b128 v[186:189], v149 offset:17408
	ds_read_b128 v[190:193], v149 offset:18432
	ds_read_b128 v[202:205], v149 offset:19456
	ds_read_b128 v[206:209], v149 offset:20480
	ds_read_b128 v[210:213], v149 offset:21504
	ds_read_b128 v[214:217], v149 offset:22528
	ds_read_b128 v[218:221], v149 offset:23552
	global_load_lds_dwordx4 v[194:195], off
	s_add_i32 m0, s4, 0x2000
	s_add_u32 vcc_lo, s38, 0x40000
	v_lshl_add_u64 v[198:199], s[38:39], 0, v[130:131]
	s_addc_u32 vcc_hi, s39, 0
	s_add_i32 s4, s65, s51
	global_load_lds_dwordx4 v[198:199], off
	v_lshl_add_u64 v[222:223], vcc, 0, v[134:135]
	s_mov_b32 m0, s4
	s_nop 0
	global_load_lds_dwordx4 v[222:223], off
	v_lshl_add_u64 v[222:223], vcc, 0, v[130:131]
	s_add_i32 m0, s4, 0x2000
	s_nop 0
	global_load_lds_dwordx4 v[222:223], off
	v_lshl_add_u64 v[222:223], s[40:41], 0, v[136:137]
	s_mov_b32 m0, s55
	s_nop 0
	global_load_lds_dwordx4 v[222:223], off
	v_lshl_add_u64 v[222:223], s[40:41], 0, v[132:133]
	s_mov_b32 m0, s56
	s_nop 0
	global_load_lds_dwordx4 v[222:223], off
	s_waitcnt vmcnt(8)
	s_waitcnt lgkmcnt(0)
	s_barrier
	s_setprio 1
	v_mfma_f32_16x16x32_bf16 v[62:65], v[150:153], v[182:185], v[62:65]
	v_mfma_f32_16x16x32_bf16 v[58:61], v[158:161], v[182:185], v[58:61]
	v_mfma_f32_16x16x32_bf16 v[46:49], v[150:153], v[190:193], v[46:49]
	v_mfma_f32_16x16x32_bf16 v[42:45], v[158:161], v[190:193], v[42:45]
	v_mfma_f32_16x16x32_bf16 v[30:33], v[150:153], v[206:209], v[30:33]
	v_mfma_f32_16x16x32_bf16 v[26:29], v[158:161], v[206:209], v[26:29]
	v_mfma_f32_16x16x32_bf16 v[14:17], v[150:153], v[214:217], v[14:17]
	v_mfma_f32_16x16x32_bf16 v[10:13], v[158:161], v[214:217], v[10:13]
	v_mfma_f32_16x16x32_bf16 v[62:65], v[154:157], v[186:189], v[62:65]
	v_mfma_f32_16x16x32_bf16 v[58:61], v[162:165], v[186:189], v[58:61]
	v_mfma_f32_16x16x32_bf16 v[46:49], v[154:157], v[202:205], v[46:49]
	v_mfma_f32_16x16x32_bf16 v[42:45], v[162:165], v[202:205], v[42:45]
	v_mfma_f32_16x16x32_bf16 v[30:33], v[154:157], v[210:213], v[30:33]
	v_mfma_f32_16x16x32_bf16 v[26:29], v[162:165], v[210:213], v[26:29]
	v_mfma_f32_16x16x32_bf16 v[14:17], v[154:157], v[218:221], v[14:17]
	v_mfma_f32_16x16x32_bf16 v[10:13], v[162:165], v[218:221], v[10:13]
	v_mfma_f32_16x16x32_bf16 v[54:57], v[166:169], v[182:185], v[54:57]
	v_mfma_f32_16x16x32_bf16 v[50:53], v[174:177], v[182:185], v[50:53]
	v_mfma_f32_16x16x32_bf16 v[38:41], v[166:169], v[190:193], v[38:41]
	v_mfma_f32_16x16x32_bf16 v[34:37], v[174:177], v[190:193], v[34:37]
	v_mfma_f32_16x16x32_bf16 v[22:25], v[166:169], v[206:209], v[22:25]
	v_mfma_f32_16x16x32_bf16 v[18:21], v[174:177], v[206:209], v[18:21]
	v_mfma_f32_16x16x32_bf16 v[6:9], v[166:169], v[214:217], v[6:9]
	v_mfma_f32_16x16x32_bf16 v[2:5], v[174:177], v[214:217], v[2:5]
	v_mfma_f32_16x16x32_bf16 v[54:57], v[170:173], v[186:189], v[54:57]
	v_mfma_f32_16x16x32_bf16 v[50:53], v[178:181], v[186:189], v[50:53]
	v_mfma_f32_16x16x32_bf16 v[38:41], v[170:173], v[202:205], v[38:41]
	v_mfma_f32_16x16x32_bf16 v[34:37], v[178:181], v[202:205], v[34:37]
	v_mfma_f32_16x16x32_bf16 v[22:25], v[170:173], v[210:213], v[22:25]
	v_mfma_f32_16x16x32_bf16 v[18:21], v[178:181], v[210:213], v[18:21]
	v_mfma_f32_16x16x32_bf16 v[6:9], v[170:173], v[218:221], v[6:9]
	v_mfma_f32_16x16x32_bf16 v[2:5], v[178:181], v[218:221], v[2:5]
	s_setprio 0
	s_barrier
	s_add_i32 s4, 0, 0x18000
	v_add_u32_e32 v0, s4, v148
	s_add_i32 s5, 0, 0x1c000
	ds_read_b128 v[150:153], v0
	ds_read_b128 v[154:157], v0 offset:1024
	ds_read_b128 v[158:161], v0 offset:2048
	ds_read_b128 v[162:165], v0 offset:3072
	v_add_u32_e32 v0, s5, v148
	ds_read_b128 v[166:169], v0
	ds_read_b128 v[170:173], v0 offset:1024
	ds_read_b128 v[174:177], v0 offset:2048
	ds_read_b128 v[178:181], v0 offset:3072
	s_add_u32 s40, s40, 0x40000
	s_addc_u32 s41, s41, 0
	s_mov_b32 m0, s57
	v_lshl_add_u64 v[222:223], s[40:41], 0, v[136:137]
	ds_read_b128 v[182:185], v149 offset:32768
	ds_read_b128 v[186:189], v149 offset:33792
	ds_read_b128 v[190:193], v149 offset:34816
	ds_read_b128 v[202:205], v149 offset:35840
	ds_read_b128 v[206:209], v149 offset:36864
	ds_read_b128 v[210:213], v149 offset:37888
	ds_read_b128 v[214:217], v149 offset:38912
	ds_read_b128 v[218:221], v149 offset:39936
	global_load_lds_dwordx4 v[222:223], off
	v_lshl_add_u64 v[222:223], s[40:41], 0, v[132:133]
	s_mov_b32 m0, s58
	s_nop 0
	global_load_lds_dwordx4 v[222:223], off
	s_waitcnt vmcnt(8)
	s_waitcnt lgkmcnt(0)
	s_barrier
	s_setprio 1
	v_mfma_f32_16x16x32_bf16 v[126:129], v[150:153], v[182:185], v[126:129]
	v_mfma_f32_16x16x32_bf16 v[122:125], v[158:161], v[182:185], v[122:125]
	v_mfma_f32_16x16x32_bf16 v[110:113], v[150:153], v[190:193], v[110:113]
	v_mfma_f32_16x16x32_bf16 v[106:109], v[158:161], v[190:193], v[106:109]
	v_mfma_f32_16x16x32_bf16 v[94:97], v[150:153], v[206:209], v[94:97]
	v_mfma_f32_16x16x32_bf16 v[90:93], v[158:161], v[206:209], v[90:93]
	v_mfma_f32_16x16x32_bf16 v[78:81], v[150:153], v[214:217], v[78:81]
	v_mfma_f32_16x16x32_bf16 v[74:77], v[158:161], v[214:217], v[74:77]
	v_mfma_f32_16x16x32_bf16 v[126:129], v[154:157], v[186:189], v[126:129]
	v_mfma_f32_16x16x32_bf16 v[122:125], v[162:165], v[186:189], v[122:125]
	v_mfma_f32_16x16x32_bf16 v[110:113], v[154:157], v[202:205], v[110:113]
	v_mfma_f32_16x16x32_bf16 v[106:109], v[162:165], v[202:205], v[106:109]
	v_mfma_f32_16x16x32_bf16 v[94:97], v[154:157], v[210:213], v[94:97]
	v_mfma_f32_16x16x32_bf16 v[90:93], v[162:165], v[210:213], v[90:93]
	v_mfma_f32_16x16x32_bf16 v[78:81], v[154:157], v[218:221], v[78:81]
	v_mfma_f32_16x16x32_bf16 v[74:77], v[162:165], v[218:221], v[74:77]
	v_mfma_f32_16x16x32_bf16 v[118:121], v[166:169], v[182:185], v[118:121]
	v_mfma_f32_16x16x32_bf16 v[114:117], v[174:177], v[182:185], v[114:117]
	v_mfma_f32_16x16x32_bf16 v[102:105], v[166:169], v[190:193], v[102:105]
	v_mfma_f32_16x16x32_bf16 v[98:101], v[174:177], v[190:193], v[98:101]
	v_mfma_f32_16x16x32_bf16 v[86:89], v[166:169], v[206:209], v[86:89]
	v_mfma_f32_16x16x32_bf16 v[82:85], v[174:177], v[206:209], v[82:85]
	v_mfma_f32_16x16x32_bf16 v[70:73], v[166:169], v[214:217], v[70:73]
	v_mfma_f32_16x16x32_bf16 v[66:69], v[174:177], v[214:217], v[66:69]
	v_mfma_f32_16x16x32_bf16 v[118:121], v[170:173], v[186:189], v[118:121]
	v_mfma_f32_16x16x32_bf16 v[114:117], v[178:181], v[186:189], v[114:117]
	v_mfma_f32_16x16x32_bf16 v[102:105], v[170:173], v[202:205], v[102:105]
	v_mfma_f32_16x16x32_bf16 v[98:101], v[178:181], v[202:205], v[98:101]
	v_mfma_f32_16x16x32_bf16 v[86:89], v[170:173], v[210:213], v[86:89]
	v_mfma_f32_16x16x32_bf16 v[82:85], v[178:181], v[210:213], v[82:85]
	v_mfma_f32_16x16x32_bf16 v[70:73], v[170:173], v[218:221], v[70:73]
	v_mfma_f32_16x16x32_bf16 v[66:69], v[178:181], v[218:221], v[66:69]
	s_setprio 0
	s_barrier
	s_add_i32 s4, s4, s51
	v_lshl_add_u64 v[194:195], v[194:195], 0, s[90:91]
	s_mov_b32 m0, s4
	ds_read_b128 v[182:185], v149 offset:49152
	ds_read_b128 v[186:189], v149 offset:50176
	ds_read_b128 v[190:193], v149 offset:51200
	ds_read_b128 v[202:205], v149 offset:52224
	ds_read_b128 v[206:209], v149 offset:53248
	ds_read_b128 v[210:213], v149 offset:54272
	ds_read_b128 v[214:217], v149 offset:55296
	ds_read_b128 v[218:221], v149 offset:56320
	global_load_lds_dwordx4 v[194:195], off
	s_add_i32 m0, s4, 0x2000
	s_add_u32 s38, s38, 0x40080
	v_lshl_add_u64 v[194:195], v[198:199], 0, s[90:91]
	s_addc_u32 s39, s39, 0
	s_add_i32 s4, s5, s51
	global_load_lds_dwordx4 v[194:195], off
	v_lshl_add_u64 v[194:195], s[38:39], 0, v[134:135]
	s_mov_b32 m0, s4
	s_nop 0
	global_load_lds_dwordx4 v[194:195], off
	v_lshl_add_u64 v[194:195], s[38:39], 0, v[130:131]
	s_add_i32 m0, s4, 0x2000
	s_nop 0
	global_load_lds_dwordx4 v[194:195], off
	v_lshl_add_u64 v[194:195], s[36:37], 0, v[136:137]
	s_mov_b32 m0, s68
	s_nop 0
	global_load_lds_dwordx4 v[194:195], off
	v_lshl_add_u64 v[194:195], s[36:37], 0, v[132:133]
	s_mov_b32 m0, s69
	s_nop 0
	global_load_lds_dwordx4 v[194:195], off
	s_waitcnt vmcnt(8)
	s_waitcnt lgkmcnt(0)
	s_barrier
	s_setprio 1
	v_mfma_f32_16x16x32_bf16 v[62:65], v[150:153], v[182:185], v[62:65]
	v_mfma_f32_16x16x32_bf16 v[58:61], v[158:161], v[182:185], v[58:61]
	v_mfma_f32_16x16x32_bf16 v[46:49], v[150:153], v[190:193], v[46:49]
	v_mfma_f32_16x16x32_bf16 v[42:45], v[158:161], v[190:193], v[42:45]
	v_mfma_f32_16x16x32_bf16 v[30:33], v[150:153], v[206:209], v[30:33]
	v_mfma_f32_16x16x32_bf16 v[26:29], v[158:161], v[206:209], v[26:29]
	v_mfma_f32_16x16x32_bf16 v[14:17], v[150:153], v[214:217], v[14:17]
	v_mfma_f32_16x16x32_bf16 v[10:13], v[158:161], v[214:217], v[10:13]
	v_mfma_f32_16x16x32_bf16 v[62:65], v[154:157], v[186:189], v[62:65]
	v_mfma_f32_16x16x32_bf16 v[58:61], v[162:165], v[186:189], v[58:61]
	v_mfma_f32_16x16x32_bf16 v[46:49], v[154:157], v[202:205], v[46:49]
	v_mfma_f32_16x16x32_bf16 v[42:45], v[162:165], v[202:205], v[42:45]
	v_mfma_f32_16x16x32_bf16 v[30:33], v[154:157], v[210:213], v[30:33]
	v_mfma_f32_16x16x32_bf16 v[26:29], v[162:165], v[210:213], v[26:29]
	v_mfma_f32_16x16x32_bf16 v[14:17], v[154:157], v[218:221], v[14:17]
	v_mfma_f32_16x16x32_bf16 v[10:13], v[162:165], v[218:221], v[10:13]
	v_mfma_f32_16x16x32_bf16 v[54:57], v[166:169], v[182:185], v[54:57]
	v_mfma_f32_16x16x32_bf16 v[50:53], v[174:177], v[182:185], v[50:53]
	v_mfma_f32_16x16x32_bf16 v[38:41], v[166:169], v[190:193], v[38:41]
	v_mfma_f32_16x16x32_bf16 v[34:37], v[174:177], v[190:193], v[34:37]
	v_mfma_f32_16x16x32_bf16 v[22:25], v[166:169], v[206:209], v[22:25]
	v_mfma_f32_16x16x32_bf16 v[18:21], v[174:177], v[206:209], v[18:21]
	v_mfma_f32_16x16x32_bf16 v[6:9], v[166:169], v[214:217], v[6:9]
	v_mfma_f32_16x16x32_bf16 v[2:5], v[174:177], v[214:217], v[2:5]
	v_mfma_f32_16x16x32_bf16 v[54:57], v[170:173], v[186:189], v[54:57]
	v_mfma_f32_16x16x32_bf16 v[50:53], v[178:181], v[186:189], v[50:53]
	v_mfma_f32_16x16x32_bf16 v[38:41], v[170:173], v[202:205], v[38:41]
	v_mfma_f32_16x16x32_bf16 v[34:37], v[178:181], v[202:205], v[34:37]
	v_mfma_f32_16x16x32_bf16 v[22:25], v[170:173], v[210:213], v[22:25]
	v_mfma_f32_16x16x32_bf16 v[18:21], v[178:181], v[210:213], v[18:21]
	v_mfma_f32_16x16x32_bf16 v[6:9], v[170:173], v[218:221], v[6:9]
	v_mfma_f32_16x16x32_bf16 v[2:5], v[178:181], v[218:221], v[2:5]
	s_setprio 0
	s_barrier
	s_add_i32 s86, s86, 2
	s_add_u32 s34, s34, 0x100
	s_addc_u32 s35, s35, 0
	s_cmp_gt_u32 s86, 13
	s_cbranch_scc0 .LBB0_675
	s_and_b64 vcc, exec, s[20:21]
	s_cbranch_vccz .LBB0_678
	s_barrier

.LBB0_773:
	s_add_u32 s4, s30, s34
	s_addc_u32 s5, s31, s35
	s_add_u32 s40, s4, 0x100
	s_addc_u32 s41, s5, 0
	s_add_u32 s38, s78, s34
	s_addc_u32 s39, s85, s35
	s_add_u32 s4, s4, 0x180
	s_addc_u32 s5, s5, 0
	s_add_i32 s65, 0, 0x10000
	s_add_i32 s87, 0, 0x14000
	v_add_u32_e32 v138, s65, v231
	v_add_u32_e32 v162, s87, v231
	ds_read_b128 v[126:129], v138
	ds_read_b128 v[130:133], v138 offset:1024
	ds_read_b128 v[134:137], v138 offset:2048
	ds_read_b128 v[138:141], v138 offset:3072
	ds_read_b128 v[142:145], v162
	ds_read_b128 v[146:149], v162 offset:1024
	ds_read_b128 v[158:161], v162 offset:2048
	ds_read_b128 v[162:165], v162 offset:3072
	s_cmpk_eq_i32 s34, 0x700
	s_cselect_b32 s37, s76, s5
	s_cselect_b32 s36, s75, s4
	s_cselect_b32 s39, s23, s39
	s_cselect_b32 s38, s74, s38
	s_cselect_b32 s41, s25, s41
	s_cselect_b32 s40, s73, s40
	v_lshl_add_u64 v[194:195], v[118:119], 0, s[34:35]
	s_add_i32 m0, s56, 0xc000
	ds_read_b128 v[166:169], v242
	ds_read_b128 v[170:173], v242 offset:1024
	ds_read_b128 v[174:177], v242 offset:2048
	ds_read_b128 v[178:181], v242 offset:3072
	ds_read_b128 v[182:185], v242 offset:4096
	ds_read_b128 v[186:189], v242 offset:5120
	ds_read_b128 v[208:211], v242 offset:6144
	ds_read_b128 v[212:215], v242 offset:7168
	global_load_lds_dwordx4 v[194:195], off
	v_lshl_add_u64 v[194:195], v[120:121], 0, s[34:35]
	s_add_i32 m0, s56, 0xe000
	s_nop 0
	global_load_lds_dwordx4 v[194:195], off
	s_waitcnt vmcnt(8)
	s_waitcnt lgkmcnt(0)
	s_barrier
	s_setprio 1
	v_mfma_f32_16x16x32_bf16 v[154:157], v[126:129], v[166:169], v[154:157]
	v_mfma_f32_16x16x32_bf16 v[150:153], v[134:137], v[166:169], v[150:153]
	v_mfma_f32_16x16x32_bf16 v[110:113], v[126:129], v[174:177], v[110:113]
	v_mfma_f32_16x16x32_bf16 v[106:109], v[134:137], v[174:177], v[106:109]
	v_mfma_f32_16x16x32_bf16 v[94:97], v[126:129], v[182:185], v[94:97]
	v_mfma_f32_16x16x32_bf16 v[90:93], v[134:137], v[182:185], v[90:93]
	v_mfma_f32_16x16x32_bf16 v[78:81], v[126:129], v[208:211], v[78:81]
	v_mfma_f32_16x16x32_bf16 v[74:77], v[134:137], v[208:211], v[74:77]
	v_mfma_f32_16x16x32_bf16 v[154:157], v[130:133], v[170:173], v[154:157]
	v_mfma_f32_16x16x32_bf16 v[150:153], v[138:141], v[170:173], v[150:153]
	v_mfma_f32_16x16x32_bf16 v[110:113], v[130:133], v[178:181], v[110:113]
	v_mfma_f32_16x16x32_bf16 v[106:109], v[138:141], v[178:181], v[106:109]
	v_mfma_f32_16x16x32_bf16 v[94:97], v[130:133], v[186:189], v[94:97]
	v_mfma_f32_16x16x32_bf16 v[90:93], v[138:141], v[186:189], v[90:93]
	v_mfma_f32_16x16x32_bf16 v[78:81], v[130:133], v[212:215], v[78:81]
	v_mfma_f32_16x16x32_bf16 v[74:77], v[138:141], v[212:215], v[74:77]
	v_mfma_f32_16x16x32_bf16 v[122:125], v[142:145], v[166:169], v[122:125]
	v_mfma_f32_16x16x32_bf16 v[114:117], v[158:161], v[166:169], v[114:117]
	v_mfma_f32_16x16x32_bf16 v[102:105], v[142:145], v[174:177], v[102:105]
	v_mfma_f32_16x16x32_bf16 v[98:101], v[158:161], v[174:177], v[98:101]
	v_mfma_f32_16x16x32_bf16 v[86:89], v[142:145], v[182:185], v[86:89]
	v_mfma_f32_16x16x32_bf16 v[82:85], v[158:161], v[182:185], v[82:85]
	v_mfma_f32_16x16x32_bf16 v[70:73], v[142:145], v[208:211], v[70:73]
	v_mfma_f32_16x16x32_bf16 v[66:69], v[158:161], v[208:211], v[66:69]
	v_mfma_f32_16x16x32_bf16 v[122:125], v[146:149], v[170:173], v[122:125]
	v_mfma_f32_16x16x32_bf16 v[114:117], v[162:165], v[170:173], v[114:117]
	v_mfma_f32_16x16x32_bf16 v[102:105], v[146:149], v[178:181], v[102:105]
	v_mfma_f32_16x16x32_bf16 v[98:101], v[162:165], v[178:181], v[98:101]
	v_mfma_f32_16x16x32_bf16 v[86:89], v[146:149], v[186:189], v[86:89]
	v_mfma_f32_16x16x32_bf16 v[82:85], v[162:165], v[186:189], v[82:85]
	v_mfma_f32_16x16x32_bf16 v[70:73], v[146:149], v[212:215], v[70:73]
	v_mfma_f32_16x16x32_bf16 v[66:69], v[162:165], v[212:215], v[66:69]
	s_setprio 0
	s_barrier
	s_add_i32 s4, s65, s51
	v_lshl_add_u64 v[194:195], s[38:39], 0, v[0:1]
	s_mov_b32 m0, s4
	ds_read_b128 v[166:169], v242 offset:16384
	ds_read_b128 v[170:173], v242 offset:17408
	ds_read_b128 v[174:177], v242 offset:18432
	ds_read_b128 v[178:181], v242 offset:19456
	ds_read_b128 v[182:185], v242 offset:20480
	ds_read_b128 v[186:189], v242 offset:21504
	ds_read_b128 v[208:211], v242 offset:22528
	ds_read_b128 v[212:215], v242 offset:23552
	global_load_lds_dwordx4 v[194:195], off
	s_add_i32 m0, s4, 0x2000
	s_add_u32 vcc_lo, s38, 0x40000
	v_lshl_add_u64 v[198:199], s[38:39], 0, v[190:191]
	s_addc_u32 vcc_hi, s39, 0
	s_add_i32 s4, s87, s51
	global_load_lds_dwordx4 v[198:199], off
	v_lshl_add_u64 v[216:217], vcc, 0, v[0:1]
	s_mov_b32 m0, s4
	s_nop 0
	global_load_lds_dwordx4 v[216:217], off
	v_lshl_add_u64 v[216:217], vcc, 0, v[190:191]
	s_add_i32 m0, s4, 0x2000
	s_nop 0
	global_load_lds_dwordx4 v[216:217], off
	v_lshl_add_u64 v[216:217], s[40:41], 0, v[202:203]
	s_mov_b32 m0, s56
	s_nop 0
	global_load_lds_dwordx4 v[216:217], off
	v_lshl_add_u64 v[216:217], s[40:41], 0, v[192:193]
	s_mov_b32 m0, s57
	s_nop 0
	global_load_lds_dwordx4 v[216:217], off
	s_waitcnt vmcnt(8)
	s_waitcnt lgkmcnt(0)
	s_barrier
	s_setprio 1
	v_mfma_f32_16x16x32_bf16 v[62:65], v[126:129], v[166:169], v[62:65]
	v_mfma_f32_16x16x32_bf16 v[58:61], v[134:137], v[166:169], v[58:61]
	v_mfma_f32_16x16x32_bf16 v[46:49], v[126:129], v[174:177], v[46:49]
	v_mfma_f32_16x16x32_bf16 v[42:45], v[134:137], v[174:177], v[42:45]
	v_mfma_f32_16x16x32_bf16 v[30:33], v[126:129], v[182:185], v[30:33]
	v_mfma_f32_16x16x32_bf16 v[26:29], v[134:137], v[182:185], v[26:29]
	v_mfma_f32_16x16x32_bf16 v[14:17], v[126:129], v[208:211], v[14:17]
	v_mfma_f32_16x16x32_bf16 v[10:13], v[134:137], v[208:211], v[10:13]
	v_mfma_f32_16x16x32_bf16 v[62:65], v[130:133], v[170:173], v[62:65]
	v_mfma_f32_16x16x32_bf16 v[58:61], v[138:141], v[170:173], v[58:61]
	v_mfma_f32_16x16x32_bf16 v[46:49], v[130:133], v[178:181], v[46:49]
	v_mfma_f32_16x16x32_bf16 v[42:45], v[138:141], v[178:181], v[42:45]
	v_mfma_f32_16x16x32_bf16 v[30:33], v[130:133], v[186:189], v[30:33]
	v_mfma_f32_16x16x32_bf16 v[26:29], v[138:141], v[186:189], v[26:29]
	v_mfma_f32_16x16x32_bf16 v[14:17], v[130:133], v[212:215], v[14:17]
	v_mfma_f32_16x16x32_bf16 v[10:13], v[138:141], v[212:215], v[10:13]
	v_mfma_f32_16x16x32_bf16 v[54:57], v[142:145], v[166:169], v[54:57]
	v_mfma_f32_16x16x32_bf16 v[50:53], v[158:161], v[166:169], v[50:53]
	v_mfma_f32_16x16x32_bf16 v[38:41], v[142:145], v[174:177], v[38:41]
	v_mfma_f32_16x16x32_bf16 v[34:37], v[158:161], v[174:177], v[34:37]
	v_mfma_f32_16x16x32_bf16 v[22:25], v[142:145], v[182:185], v[22:25]
	v_mfma_f32_16x16x32_bf16 v[18:21], v[158:161], v[182:185], v[18:21]
	v_mfma_f32_16x16x32_bf16 v[6:9], v[142:145], v[208:211], v[6:9]
	v_mfma_f32_16x16x32_bf16 v[2:5], v[158:161], v[208:211], v[2:5]
	v_mfma_f32_16x16x32_bf16 v[54:57], v[146:149], v[170:173], v[54:57]
	v_mfma_f32_16x16x32_bf16 v[50:53], v[162:165], v[170:173], v[50:53]
	v_mfma_f32_16x16x32_bf16 v[38:41], v[146:149], v[178:181], v[38:41]
	v_mfma_f32_16x16x32_bf16 v[34:37], v[162:165], v[178:181], v[34:37]
	v_mfma_f32_16x16x32_bf16 v[22:25], v[146:149], v[186:189], v[22:25]
	v_mfma_f32_16x16x32_bf16 v[18:21], v[162:165], v[186:189], v[18:21]
	v_mfma_f32_16x16x32_bf16 v[6:9], v[146:149], v[212:215], v[6:9]
	v_mfma_f32_16x16x32_bf16 v[2:5], v[162:165], v[212:215], v[2:5]
	s_setprio 0
	s_barrier
	s_add_i32 s4, 0, 0x18000
	s_add_i32 s5, 0, 0x1c000
	v_add_u32_e32 v138, s4, v231
	v_add_u32_e32 v162, s5, v231
	ds_read_b128 v[126:129], v138
	ds_read_b128 v[130:133], v138 offset:1024
	ds_read_b128 v[134:137], v138 offset:2048
	ds_read_b128 v[138:141], v138 offset:3072
	ds_read_b128 v[142:145], v162
	ds_read_b128 v[146:149], v162 offset:1024
	ds_read_b128 v[158:161], v162 offset:2048
	ds_read_b128 v[162:165], v162 offset:3072
	s_add_u32 s40, s40, 0x40000
	s_addc_u32 s41, s41, 0
	s_mov_b32 m0, s58
	v_lshl_add_u64 v[216:217], s[40:41], 0, v[202:203]
	ds_read_b128 v[166:169], v242 offset:32768
	ds_read_b128 v[170:173], v242 offset:33792
	ds_read_b128 v[174:177], v242 offset:34816
	ds_read_b128 v[178:181], v242 offset:35840
	ds_read_b128 v[182:185], v242 offset:36864
	ds_read_b128 v[186:189], v242 offset:37888
	ds_read_b128 v[208:211], v242 offset:38912
	ds_read_b128 v[212:215], v242 offset:39936
	global_load_lds_dwordx4 v[216:217], off
	v_lshl_add_u64 v[216:217], s[40:41], 0, v[192:193]
	s_mov_b32 m0, s59
	s_nop 0
	global_load_lds_dwordx4 v[216:217], off
	s_waitcnt vmcnt(8)
	s_waitcnt lgkmcnt(0)
	s_barrier
	s_setprio 1
	v_mfma_f32_16x16x32_bf16 v[154:157], v[126:129], v[166:169], v[154:157]
	v_mfma_f32_16x16x32_bf16 v[150:153], v[134:137], v[166:169], v[150:153]
	v_mfma_f32_16x16x32_bf16 v[110:113], v[126:129], v[174:177], v[110:113]
	v_mfma_f32_16x16x32_bf16 v[106:109], v[134:137], v[174:177], v[106:109]
	v_mfma_f32_16x16x32_bf16 v[94:97], v[126:129], v[182:185], v[94:97]
	v_mfma_f32_16x16x32_bf16 v[90:93], v[134:137], v[182:185], v[90:93]
	v_mfma_f32_16x16x32_bf16 v[78:81], v[126:129], v[208:211], v[78:81]
	v_mfma_f32_16x16x32_bf16 v[74:77], v[134:137], v[208:211], v[74:77]
	v_mfma_f32_16x16x32_bf16 v[154:157], v[130:133], v[170:173], v[154:157]
	v_mfma_f32_16x16x32_bf16 v[150:153], v[138:141], v[170:173], v[150:153]
	v_mfma_f32_16x16x32_bf16 v[110:113], v[130:133], v[178:181], v[110:113]
	v_mfma_f32_16x16x32_bf16 v[106:109], v[138:141], v[178:181], v[106:109]
	v_mfma_f32_16x16x32_bf16 v[94:97], v[130:133], v[186:189], v[94:97]
	v_mfma_f32_16x16x32_bf16 v[90:93], v[138:141], v[186:189], v[90:93]
	v_mfma_f32_16x16x32_bf16 v[78:81], v[130:133], v[212:215], v[78:81]
	v_mfma_f32_16x16x32_bf16 v[74:77], v[138:141], v[212:215], v[74:77]
	v_mfma_f32_16x16x32_bf16 v[122:125], v[142:145], v[166:169], v[122:125]
	v_mfma_f32_16x16x32_bf16 v[114:117], v[158:161], v[166:169], v[114:117]
	v_mfma_f32_16x16x32_bf16 v[102:105], v[142:145], v[174:177], v[102:105]
	v_mfma_f32_16x16x32_bf16 v[98:101], v[158:161], v[174:177], v[98:101]
	v_mfma_f32_16x16x32_bf16 v[86:89], v[142:145], v[182:185], v[86:89]
	v_mfma_f32_16x16x32_bf16 v[82:85], v[158:161], v[182:185], v[82:85]
	v_mfma_f32_16x16x32_bf16 v[70:73], v[142:145], v[208:211], v[70:73]
	v_mfma_f32_16x16x32_bf16 v[66:69], v[158:161], v[208:211], v[66:69]
	v_mfma_f32_16x16x32_bf16 v[122:125], v[146:149], v[170:173], v[122:125]
	v_mfma_f32_16x16x32_bf16 v[114:117], v[162:165], v[170:173], v[114:117]
	v_mfma_f32_16x16x32_bf16 v[102:105], v[146:149], v[178:181], v[102:105]
	v_mfma_f32_16x16x32_bf16 v[98:101], v[162:165], v[178:181], v[98:101]
	v_mfma_f32_16x16x32_bf16 v[86:89], v[146:149], v[186:189], v[86:89]
	v_mfma_f32_16x16x32_bf16 v[82:85], v[162:165], v[186:189], v[82:85]
	v_mfma_f32_16x16x32_bf16 v[70:73], v[146:149], v[212:215], v[70:73]
	v_mfma_f32_16x16x32_bf16 v[66:69], v[162:165], v[212:215], v[66:69]
	s_setprio 0
	s_barrier
	s_add_i32 s4, s4, s51
	v_lshl_add_u64 v[194:195], v[194:195], 0, s[90:91]
	s_mov_b32 m0, s4
	ds_read_b128 v[166:169], v242 offset:49152
	ds_read_b128 v[170:173], v242 offset:50176
	ds_read_b128 v[174:177], v242 offset:51200
	ds_read_b128 v[178:181], v242 offset:52224
	ds_read_b128 v[182:185], v242 offset:53248
	ds_read_b128 v[186:189], v242 offset:54272
	ds_read_b128 v[208:211], v242 offset:55296
	ds_read_b128 v[212:215], v242 offset:56320
	global_load_lds_dwordx4 v[194:195], off
	s_add_i32 m0, s4, 0x2000
	s_add_u32 s38, s38, 0x40080
	v_lshl_add_u64 v[194:195], v[198:199], 0, s[90:91]
	s_addc_u32 s39, s39, 0
	s_add_i32 s4, s5, s51
	global_load_lds_dwordx4 v[194:195], off
	v_lshl_add_u64 v[194:195], s[38:39], 0, v[0:1]
	s_mov_b32 m0, s4
	s_nop 0
	global_load_lds_dwordx4 v[194:195], off
	v_lshl_add_u64 v[194:195], s[38:39], 0, v[190:191]
	s_add_i32 m0, s4, 0x2000
	s_nop 0
	global_load_lds_dwordx4 v[194:195], off
	v_lshl_add_u64 v[194:195], s[36:37], 0, v[202:203]
	s_mov_b32 m0, s68
	s_nop 0
	global_load_lds_dwordx4 v[194:195], off
	v_lshl_add_u64 v[194:195], s[36:37], 0, v[192:193]
	s_mov_b32 m0, s69
	s_nop 0
	global_load_lds_dwordx4 v[194:195], off
	s_waitcnt vmcnt(8)
	s_waitcnt lgkmcnt(0)
	s_barrier
	s_setprio 1
	v_mfma_f32_16x16x32_bf16 v[62:65], v[126:129], v[166:169], v[62:65]
	v_mfma_f32_16x16x32_bf16 v[58:61], v[134:137], v[166:169], v[58:61]
	v_mfma_f32_16x16x32_bf16 v[46:49], v[126:129], v[174:177], v[46:49]
	v_mfma_f32_16x16x32_bf16 v[42:45], v[134:137], v[174:177], v[42:45]
	v_mfma_f32_16x16x32_bf16 v[30:33], v[126:129], v[182:185], v[30:33]
	v_mfma_f32_16x16x32_bf16 v[26:29], v[134:137], v[182:185], v[26:29]
	v_mfma_f32_16x16x32_bf16 v[14:17], v[126:129], v[208:211], v[14:17]
	v_mfma_f32_16x16x32_bf16 v[10:13], v[134:137], v[208:211], v[10:13]
	v_mfma_f32_16x16x32_bf16 v[62:65], v[130:133], v[170:173], v[62:65]
	v_mfma_f32_16x16x32_bf16 v[58:61], v[138:141], v[170:173], v[58:61]
	v_mfma_f32_16x16x32_bf16 v[46:49], v[130:133], v[178:181], v[46:49]
	v_mfma_f32_16x16x32_bf16 v[42:45], v[138:141], v[178:181], v[42:45]
	v_mfma_f32_16x16x32_bf16 v[30:33], v[130:133], v[186:189], v[30:33]
	v_mfma_f32_16x16x32_bf16 v[26:29], v[138:141], v[186:189], v[26:29]
	v_mfma_f32_16x16x32_bf16 v[14:17], v[130:133], v[212:215], v[14:17]
	v_mfma_f32_16x16x32_bf16 v[10:13], v[138:141], v[212:215], v[10:13]
	v_mfma_f32_16x16x32_bf16 v[54:57], v[142:145], v[166:169], v[54:57]
	v_mfma_f32_16x16x32_bf16 v[50:53], v[158:161], v[166:169], v[50:53]
	v_mfma_f32_16x16x32_bf16 v[38:41], v[142:145], v[174:177], v[38:41]
	v_mfma_f32_16x16x32_bf16 v[34:37], v[158:161], v[174:177], v[34:37]
	v_mfma_f32_16x16x32_bf16 v[22:25], v[142:145], v[182:185], v[22:25]
	v_mfma_f32_16x16x32_bf16 v[18:21], v[158:161], v[182:185], v[18:21]
	v_mfma_f32_16x16x32_bf16 v[6:9], v[142:145], v[208:211], v[6:9]
	v_mfma_f32_16x16x32_bf16 v[2:5], v[158:161], v[208:211], v[2:5]
	v_mfma_f32_16x16x32_bf16 v[54:57], v[146:149], v[170:173], v[54:57]
	v_mfma_f32_16x16x32_bf16 v[50:53], v[162:165], v[170:173], v[50:53]
	v_mfma_f32_16x16x32_bf16 v[38:41], v[146:149], v[178:181], v[38:41]
	v_mfma_f32_16x16x32_bf16 v[34:37], v[162:165], v[178:181], v[34:37]
	v_mfma_f32_16x16x32_bf16 v[22:25], v[146:149], v[186:189], v[22:25]
	v_mfma_f32_16x16x32_bf16 v[18:21], v[162:165], v[186:189], v[18:21]
	v_mfma_f32_16x16x32_bf16 v[6:9], v[146:149], v[212:215], v[6:9]
	v_mfma_f32_16x16x32_bf16 v[2:5], v[162:165], v[212:215], v[2:5]
	s_setprio 0
	s_barrier
	s_add_i32 s86, s86, 2
	s_add_u32 s34, s34, 0x100
	s_addc_u32 s35, s35, 0
	s_cmp_gt_u32 s86, 13
	s_cbranch_scc0 .LBB0_773
	s_and_b64 vcc, exec, s[18:19]
	s_cbranch_vccz .LBB0_776
	s_barrier

.LBB0_861:
	s_add_u32 s4, s30, s34
	s_addc_u32 s5, s31, s35
	s_add_u32 s40, s4, 0x100
	s_addc_u32 s41, s5, 0
	s_add_u32 s38, s78, s34
	s_addc_u32 s39, s85, s35
	s_add_u32 s4, s4, 0x180
	s_addc_u32 s5, s5, 0
	s_add_i32 s65, 0, 0x10000
	s_add_i32 s87, 0, 0x14000
	v_add_u32_e32 v162, s65, v152
	v_add_u32_e32 v178, s87, v152
	ds_read_b128 v[146:149], v162
	ds_read_b128 v[154:157], v162 offset:1024
	ds_read_b128 v[158:161], v162 offset:2048
	ds_read_b128 v[162:165], v162 offset:3072
	ds_read_b128 v[166:169], v178
	ds_read_b128 v[170:173], v178 offset:1024
	ds_read_b128 v[174:177], v178 offset:2048
	ds_read_b128 v[178:181], v178 offset:3072
	s_cmpk_eq_i32 s34, 0x700
	s_cselect_b32 s37, s76, s5
	s_cselect_b32 s36, s75, s4
	s_cselect_b32 s39, s23, s39
	s_cselect_b32 s38, s74, s38
	s_cselect_b32 s41, s25, s41
	s_cselect_b32 s40, s73, s40
	v_lshl_add_u64 v[194:195], v[142:143], 0, s[34:35]
	s_add_i32 m0, s56, 0xc000
	ds_read_b128 v[182:185], v153
	ds_read_b128 v[186:189], v153 offset:1024
	ds_read_b128 v[190:193], v153 offset:2048
	ds_read_b128 v[202:205], v153 offset:3072
	ds_read_b128 v[206:209], v153 offset:4096
	ds_read_b128 v[210:213], v153 offset:5120
	ds_read_b128 v[214:217], v153 offset:6144
	ds_read_b128 v[218:221], v153 offset:7168
	global_load_lds_dwordx4 v[194:195], off
	v_lshl_add_u64 v[194:195], v[144:145], 0, s[34:35]
	s_add_i32 m0, s56, 0xe000
	s_nop 0
	global_load_lds_dwordx4 v[194:195], off
	s_waitcnt vmcnt(8)
	s_waitcnt lgkmcnt(0)
	s_barrier
	s_setprio 1
	v_mfma_f32_16x16x32_bf16 v[126:129], v[146:149], v[182:185], v[126:129]
	v_mfma_f32_16x16x32_bf16 v[122:125], v[158:161], v[182:185], v[122:125]
	v_mfma_f32_16x16x32_bf16 v[110:113], v[146:149], v[190:193], v[110:113]
	v_mfma_f32_16x16x32_bf16 v[106:109], v[158:161], v[190:193], v[106:109]
	v_mfma_f32_16x16x32_bf16 v[94:97], v[146:149], v[206:209], v[94:97]
	v_mfma_f32_16x16x32_bf16 v[90:93], v[158:161], v[206:209], v[90:93]
	v_mfma_f32_16x16x32_bf16 v[78:81], v[146:149], v[214:217], v[78:81]
	v_mfma_f32_16x16x32_bf16 v[74:77], v[158:161], v[214:217], v[74:77]
	v_mfma_f32_16x16x32_bf16 v[126:129], v[154:157], v[186:189], v[126:129]
	v_mfma_f32_16x16x32_bf16 v[122:125], v[162:165], v[186:189], v[122:125]
	v_mfma_f32_16x16x32_bf16 v[110:113], v[154:157], v[202:205], v[110:113]
	v_mfma_f32_16x16x32_bf16 v[106:109], v[162:165], v[202:205], v[106:109]
	v_mfma_f32_16x16x32_bf16 v[94:97], v[154:157], v[210:213], v[94:97]
	v_mfma_f32_16x16x32_bf16 v[90:93], v[162:165], v[210:213], v[90:93]
	v_mfma_f32_16x16x32_bf16 v[78:81], v[154:157], v[218:221], v[78:81]
	v_mfma_f32_16x16x32_bf16 v[74:77], v[162:165], v[218:221], v[74:77]
	v_mfma_f32_16x16x32_bf16 v[118:121], v[166:169], v[182:185], v[118:121]
	v_mfma_f32_16x16x32_bf16 v[114:117], v[174:177], v[182:185], v[114:117]
	v_mfma_f32_16x16x32_bf16 v[102:105], v[166:169], v[190:193], v[102:105]
	v_mfma_f32_16x16x32_bf16 v[98:101], v[174:177], v[190:193], v[98:101]
	v_mfma_f32_16x16x32_bf16 v[86:89], v[166:169], v[206:209], v[86:89]
	v_mfma_f32_16x16x32_bf16 v[82:85], v[174:177], v[206:209], v[82:85]
	v_mfma_f32_16x16x32_bf16 v[70:73], v[166:169], v[214:217], v[70:73]
	v_mfma_f32_16x16x32_bf16 v[66:69], v[174:177], v[214:217], v[66:69]
	v_mfma_f32_16x16x32_bf16 v[118:121], v[170:173], v[186:189], v[118:121]
	v_mfma_f32_16x16x32_bf16 v[114:117], v[178:181], v[186:189], v[114:117]
	v_mfma_f32_16x16x32_bf16 v[102:105], v[170:173], v[202:205], v[102:105]
	v_mfma_f32_16x16x32_bf16 v[98:101], v[178:181], v[202:205], v[98:101]
	v_mfma_f32_16x16x32_bf16 v[86:89], v[170:173], v[210:213], v[86:89]
	v_mfma_f32_16x16x32_bf16 v[82:85], v[178:181], v[210:213], v[82:85]
	v_mfma_f32_16x16x32_bf16 v[70:73], v[170:173], v[218:221], v[70:73]
	v_mfma_f32_16x16x32_bf16 v[66:69], v[178:181], v[218:221], v[66:69]
	s_setprio 0
	s_barrier
	s_add_i32 s4, s65, s51
	v_lshl_add_u64 v[194:195], s[38:39], 0, v[134:135]
	s_mov_b32 m0, s4
	ds_read_b128 v[182:185], v153 offset:16384
	ds_read_b128 v[186:189], v153 offset:17408
	ds_read_b128 v[190:193], v153 offset:18432
	ds_read_b128 v[202:205], v153 offset:19456
	ds_read_b128 v[206:209], v153 offset:20480
	ds_read_b128 v[210:213], v153 offset:21504
	ds_read_b128 v[214:217], v153 offset:22528
	ds_read_b128 v[218:221], v153 offset:23552
	global_load_lds_dwordx4 v[194:195], off
	s_add_i32 m0, s4, 0x2000
	s_add_u32 vcc_lo, s38, 0x40000
	v_lshl_add_u64 v[198:199], s[38:39], 0, v[130:131]
	s_addc_u32 vcc_hi, s39, 0
	s_add_i32 s4, s87, s51
	global_load_lds_dwordx4 v[198:199], off
	v_lshl_add_u64 v[222:223], vcc, 0, v[134:135]
	s_mov_b32 m0, s4
	s_nop 0
	global_load_lds_dwordx4 v[222:223], off
	v_lshl_add_u64 v[222:223], vcc, 0, v[130:131]
	s_add_i32 m0, s4, 0x2000
	s_nop 0
	global_load_lds_dwordx4 v[222:223], off
	v_lshl_add_u64 v[222:223], s[40:41], 0, v[136:137]
	s_mov_b32 m0, s56
	s_nop 0
	global_load_lds_dwordx4 v[222:223], off
	v_lshl_add_u64 v[222:223], s[40:41], 0, v[132:133]
	s_mov_b32 m0, s57
	s_nop 0
	global_load_lds_dwordx4 v[222:223], off
	s_waitcnt vmcnt(8)
	s_waitcnt lgkmcnt(0)
	s_barrier
	s_setprio 1
	v_mfma_f32_16x16x32_bf16 v[62:65], v[146:149], v[182:185], v[62:65]
	v_mfma_f32_16x16x32_bf16 v[58:61], v[158:161], v[182:185], v[58:61]
	v_mfma_f32_16x16x32_bf16 v[46:49], v[146:149], v[190:193], v[46:49]
	v_mfma_f32_16x16x32_bf16 v[42:45], v[158:161], v[190:193], v[42:45]
	v_mfma_f32_16x16x32_bf16 v[30:33], v[146:149], v[206:209], v[30:33]
	v_mfma_f32_16x16x32_bf16 v[26:29], v[158:161], v[206:209], v[26:29]
	v_mfma_f32_16x16x32_bf16 v[14:17], v[146:149], v[214:217], v[14:17]
	v_mfma_f32_16x16x32_bf16 v[10:13], v[158:161], v[214:217], v[10:13]
	v_mfma_f32_16x16x32_bf16 v[62:65], v[154:157], v[186:189], v[62:65]
	v_mfma_f32_16x16x32_bf16 v[58:61], v[162:165], v[186:189], v[58:61]
	v_mfma_f32_16x16x32_bf16 v[46:49], v[154:157], v[202:205], v[46:49]
	v_mfma_f32_16x16x32_bf16 v[42:45], v[162:165], v[202:205], v[42:45]
	v_mfma_f32_16x16x32_bf16 v[30:33], v[154:157], v[210:213], v[30:33]
	v_mfma_f32_16x16x32_bf16 v[26:29], v[162:165], v[210:213], v[26:29]
	v_mfma_f32_16x16x32_bf16 v[14:17], v[154:157], v[218:221], v[14:17]
	v_mfma_f32_16x16x32_bf16 v[10:13], v[162:165], v[218:221], v[10:13]
	v_mfma_f32_16x16x32_bf16 v[54:57], v[166:169], v[182:185], v[54:57]
	v_mfma_f32_16x16x32_bf16 v[50:53], v[174:177], v[182:185], v[50:53]
	v_mfma_f32_16x16x32_bf16 v[38:41], v[166:169], v[190:193], v[38:41]
	v_mfma_f32_16x16x32_bf16 v[34:37], v[174:177], v[190:193], v[34:37]
	v_mfma_f32_16x16x32_bf16 v[22:25], v[166:169], v[206:209], v[22:25]
	v_mfma_f32_16x16x32_bf16 v[18:21], v[174:177], v[206:209], v[18:21]
	v_mfma_f32_16x16x32_bf16 v[6:9], v[166:169], v[214:217], v[6:9]
	v_mfma_f32_16x16x32_bf16 v[2:5], v[174:177], v[214:217], v[2:5]
	v_mfma_f32_16x16x32_bf16 v[54:57], v[170:173], v[186:189], v[54:57]
	v_mfma_f32_16x16x32_bf16 v[50:53], v[178:181], v[186:189], v[50:53]
	v_mfma_f32_16x16x32_bf16 v[38:41], v[170:173], v[202:205], v[38:41]
	v_mfma_f32_16x16x32_bf16 v[34:37], v[178:181], v[202:205], v[34:37]
	v_mfma_f32_16x16x32_bf16 v[22:25], v[170:173], v[210:213], v[22:25]
	v_mfma_f32_16x16x32_bf16 v[18:21], v[178:181], v[210:213], v[18:21]
	v_mfma_f32_16x16x32_bf16 v[6:9], v[170:173], v[218:221], v[6:9]
	v_mfma_f32_16x16x32_bf16 v[2:5], v[178:181], v[218:221], v[2:5]
	s_setprio 0
	s_barrier
	s_add_i32 s4, 0, 0x18000
	s_add_i32 s5, 0, 0x1c000
	v_add_u32_e32 v162, s4, v152
	v_add_u32_e32 v178, s5, v152
	ds_read_b128 v[146:149], v162
	ds_read_b128 v[154:157], v162 offset:1024
	ds_read_b128 v[158:161], v162 offset:2048
	ds_read_b128 v[162:165], v162 offset:3072
	ds_read_b128 v[166:169], v178
	ds_read_b128 v[170:173], v178 offset:1024
	ds_read_b128 v[174:177], v178 offset:2048
	ds_read_b128 v[178:181], v178 offset:3072
	s_add_u32 s40, s40, 0x40000
	s_addc_u32 s41, s41, 0
	s_mov_b32 m0, s58
	v_lshl_add_u64 v[222:223], s[40:41], 0, v[136:137]
	ds_read_b128 v[182:185], v153 offset:32768
	ds_read_b128 v[186:189], v153 offset:33792
	ds_read_b128 v[190:193], v153 offset:34816
	ds_read_b128 v[202:205], v153 offset:35840
	ds_read_b128 v[206:209], v153 offset:36864
	ds_read_b128 v[210:213], v153 offset:37888
	ds_read_b128 v[214:217], v153 offset:38912
	ds_read_b128 v[218:221], v153 offset:39936
	global_load_lds_dwordx4 v[222:223], off
	v_lshl_add_u64 v[222:223], s[40:41], 0, v[132:133]
	s_mov_b32 m0, s59
	s_nop 0
	global_load_lds_dwordx4 v[222:223], off
	s_waitcnt vmcnt(8)
	s_waitcnt lgkmcnt(0)
	s_barrier
	s_setprio 1
	v_mfma_f32_16x16x32_bf16 v[126:129], v[146:149], v[182:185], v[126:129]
	v_mfma_f32_16x16x32_bf16 v[122:125], v[158:161], v[182:185], v[122:125]
	v_mfma_f32_16x16x32_bf16 v[110:113], v[146:149], v[190:193], v[110:113]
	v_mfma_f32_16x16x32_bf16 v[106:109], v[158:161], v[190:193], v[106:109]
	v_mfma_f32_16x16x32_bf16 v[94:97], v[146:149], v[206:209], v[94:97]
	v_mfma_f32_16x16x32_bf16 v[90:93], v[158:161], v[206:209], v[90:93]
	v_mfma_f32_16x16x32_bf16 v[78:81], v[146:149], v[214:217], v[78:81]
	v_mfma_f32_16x16x32_bf16 v[74:77], v[158:161], v[214:217], v[74:77]
	v_mfma_f32_16x16x32_bf16 v[126:129], v[154:157], v[186:189], v[126:129]
	v_mfma_f32_16x16x32_bf16 v[122:125], v[162:165], v[186:189], v[122:125]
	v_mfma_f32_16x16x32_bf16 v[110:113], v[154:157], v[202:205], v[110:113]
	v_mfma_f32_16x16x32_bf16 v[106:109], v[162:165], v[202:205], v[106:109]
	v_mfma_f32_16x16x32_bf16 v[94:97], v[154:157], v[210:213], v[94:97]
	v_mfma_f32_16x16x32_bf16 v[90:93], v[162:165], v[210:213], v[90:93]
	v_mfma_f32_16x16x32_bf16 v[78:81], v[154:157], v[218:221], v[78:81]
	v_mfma_f32_16x16x32_bf16 v[74:77], v[162:165], v[218:221], v[74:77]
	v_mfma_f32_16x16x32_bf16 v[118:121], v[166:169], v[182:185], v[118:121]
	v_mfma_f32_16x16x32_bf16 v[114:117], v[174:177], v[182:185], v[114:117]
	v_mfma_f32_16x16x32_bf16 v[102:105], v[166:169], v[190:193], v[102:105]
	v_mfma_f32_16x16x32_bf16 v[98:101], v[174:177], v[190:193], v[98:101]
	v_mfma_f32_16x16x32_bf16 v[86:89], v[166:169], v[206:209], v[86:89]
	v_mfma_f32_16x16x32_bf16 v[82:85], v[174:177], v[206:209], v[82:85]
	v_mfma_f32_16x16x32_bf16 v[70:73], v[166:169], v[214:217], v[70:73]
	v_mfma_f32_16x16x32_bf16 v[66:69], v[174:177], v[214:217], v[66:69]
	v_mfma_f32_16x16x32_bf16 v[118:121], v[170:173], v[186:189], v[118:121]
	v_mfma_f32_16x16x32_bf16 v[114:117], v[178:181], v[186:189], v[114:117]
	v_mfma_f32_16x16x32_bf16 v[102:105], v[170:173], v[202:205], v[102:105]
	v_mfma_f32_16x16x32_bf16 v[98:101], v[178:181], v[202:205], v[98:101]
	v_mfma_f32_16x16x32_bf16 v[86:89], v[170:173], v[210:213], v[86:89]
	v_mfma_f32_16x16x32_bf16 v[82:85], v[178:181], v[210:213], v[82:85]
	v_mfma_f32_16x16x32_bf16 v[70:73], v[170:173], v[218:221], v[70:73]
	v_mfma_f32_16x16x32_bf16 v[66:69], v[178:181], v[218:221], v[66:69]
	s_setprio 0
	s_barrier
	s_add_i32 s4, s4, s51
	v_lshl_add_u64 v[194:195], v[194:195], 0, s[90:91]
	s_mov_b32 m0, s4
	ds_read_b128 v[182:185], v153 offset:49152
	ds_read_b128 v[186:189], v153 offset:50176
	ds_read_b128 v[190:193], v153 offset:51200
	ds_read_b128 v[202:205], v153 offset:52224
	ds_read_b128 v[206:209], v153 offset:53248
	ds_read_b128 v[210:213], v153 offset:54272
	ds_read_b128 v[214:217], v153 offset:55296
	ds_read_b128 v[218:221], v153 offset:56320
	global_load_lds_dwordx4 v[194:195], off
	s_add_i32 m0, s4, 0x2000
	s_add_u32 s38, s38, 0x40080
	v_lshl_add_u64 v[194:195], v[198:199], 0, s[90:91]
	s_addc_u32 s39, s39, 0
	s_add_i32 s4, s5, s51
	global_load_lds_dwordx4 v[194:195], off
	v_lshl_add_u64 v[194:195], s[38:39], 0, v[134:135]
	s_mov_b32 m0, s4
	s_nop 0
	global_load_lds_dwordx4 v[194:195], off
	v_lshl_add_u64 v[194:195], s[38:39], 0, v[130:131]
	s_add_i32 m0, s4, 0x2000
	s_nop 0
	global_load_lds_dwordx4 v[194:195], off
	v_lshl_add_u64 v[194:195], s[36:37], 0, v[136:137]
	s_mov_b32 m0, s68
	s_nop 0
	global_load_lds_dwordx4 v[194:195], off
	v_lshl_add_u64 v[194:195], s[36:37], 0, v[132:133]
	s_mov_b32 m0, s69
	s_nop 0
	global_load_lds_dwordx4 v[194:195], off
	s_waitcnt vmcnt(8)
	s_waitcnt lgkmcnt(0)
	s_barrier
	s_setprio 1
	v_mfma_f32_16x16x32_bf16 v[62:65], v[146:149], v[182:185], v[62:65]
	v_mfma_f32_16x16x32_bf16 v[58:61], v[158:161], v[182:185], v[58:61]
	v_mfma_f32_16x16x32_bf16 v[46:49], v[146:149], v[190:193], v[46:49]
	v_mfma_f32_16x16x32_bf16 v[42:45], v[158:161], v[190:193], v[42:45]
	v_mfma_f32_16x16x32_bf16 v[30:33], v[146:149], v[206:209], v[30:33]
	v_mfma_f32_16x16x32_bf16 v[26:29], v[158:161], v[206:209], v[26:29]
	v_mfma_f32_16x16x32_bf16 v[14:17], v[146:149], v[214:217], v[14:17]
	v_mfma_f32_16x16x32_bf16 v[10:13], v[158:161], v[214:217], v[10:13]
	v_mfma_f32_16x16x32_bf16 v[62:65], v[154:157], v[186:189], v[62:65]
	v_mfma_f32_16x16x32_bf16 v[58:61], v[162:165], v[186:189], v[58:61]
	v_mfma_f32_16x16x32_bf16 v[46:49], v[154:157], v[202:205], v[46:49]
	v_mfma_f32_16x16x32_bf16 v[42:45], v[162:165], v[202:205], v[42:45]
	v_mfma_f32_16x16x32_bf16 v[30:33], v[154:157], v[210:213], v[30:33]
	v_mfma_f32_16x16x32_bf16 v[26:29], v[162:165], v[210:213], v[26:29]
	v_mfma_f32_16x16x32_bf16 v[14:17], v[154:157], v[218:221], v[14:17]
	v_mfma_f32_16x16x32_bf16 v[10:13], v[162:165], v[218:221], v[10:13]
	v_mfma_f32_16x16x32_bf16 v[54:57], v[166:169], v[182:185], v[54:57]
	v_mfma_f32_16x16x32_bf16 v[50:53], v[174:177], v[182:185], v[50:53]
	v_mfma_f32_16x16x32_bf16 v[38:41], v[166:169], v[190:193], v[38:41]
	v_mfma_f32_16x16x32_bf16 v[34:37], v[174:177], v[190:193], v[34:37]
	v_mfma_f32_16x16x32_bf16 v[22:25], v[166:169], v[206:209], v[22:25]
	v_mfma_f32_16x16x32_bf16 v[18:21], v[174:177], v[206:209], v[18:21]
	v_mfma_f32_16x16x32_bf16 v[6:9], v[166:169], v[214:217], v[6:9]
	v_mfma_f32_16x16x32_bf16 v[2:5], v[174:177], v[214:217], v[2:5]
	v_mfma_f32_16x16x32_bf16 v[54:57], v[170:173], v[186:189], v[54:57]
	v_mfma_f32_16x16x32_bf16 v[50:53], v[178:181], v[186:189], v[50:53]
	v_mfma_f32_16x16x32_bf16 v[38:41], v[170:173], v[202:205], v[38:41]
	v_mfma_f32_16x16x32_bf16 v[34:37], v[178:181], v[202:205], v[34:37]
	v_mfma_f32_16x16x32_bf16 v[22:25], v[170:173], v[210:213], v[22:25]
	v_mfma_f32_16x16x32_bf16 v[18:21], v[178:181], v[210:213], v[18:21]
	v_mfma_f32_16x16x32_bf16 v[6:9], v[170:173], v[218:221], v[6:9]
	v_mfma_f32_16x16x32_bf16 v[2:5], v[178:181], v[218:221], v[2:5]
	s_setprio 0
	s_barrier
	s_add_i32 s86, s86, 2
	s_add_u32 s34, s34, 0x100
	s_addc_u32 s35, s35, 0
	s_cmp_gt_u32 s86, 13
	s_cbranch_scc0 .LBB0_861
	s_and_b64 vcc, exec, s[20:21]
	s_cbranch_vccz .LBB0_864
	s_barrier

.LBB0_915:
	s_add_u32 s4, s34, s36
	s_addc_u32 s5, s35, s37
	s_add_u32 s42, s4, 0x100
	s_addc_u32 s43, s5, 0
	s_add_u32 s40, s76, s36
	s_addc_u32 s41, s78, s37
	s_add_u32 s4, s4, 0x180
	s_addc_u32 s5, s5, 0
	s_add_i32 s85, 0, 0x10000
	s_add_i32 vcc_lo, 0, 0x14000
	v_add_u32_e32 v138, s85, v231
	v_add_u32_e32 v162, vcc_lo, v231
	ds_read_b128 v[126:129], v138
	ds_read_b128 v[130:133], v138 offset:1024
	ds_read_b128 v[134:137], v138 offset:2048
	ds_read_b128 v[138:141], v138 offset:3072
	ds_read_b128 v[142:145], v162
	ds_read_b128 v[146:149], v162 offset:1024
	ds_read_b128 v[158:161], v162 offset:2048
	ds_read_b128 v[162:165], v162 offset:3072
	s_cmpk_eq_i32 s36, 0x1f00
	s_cselect_b32 s39, s75, s5
	s_cselect_b32 s38, s74, s4
	s_cselect_b32 s41, s25, s41
	s_cselect_b32 s40, s73, s40
	s_cselect_b32 s43, s27, s43
	s_cselect_b32 s42, s72, s42
	v_lshl_add_u64 v[194:195], v[118:119], 0, s[36:37]
	s_add_i32 m0, s58, 0xc000
	ds_read_b128 v[166:169], v242
	ds_read_b128 v[170:173], v242 offset:1024
	ds_read_b128 v[174:177], v242 offset:2048
	ds_read_b128 v[178:181], v242 offset:3072
	ds_read_b128 v[182:185], v242 offset:4096
	ds_read_b128 v[186:189], v242 offset:5120
	ds_read_b128 v[208:211], v242 offset:6144
	ds_read_b128 v[212:215], v242 offset:7168
	global_load_lds_dwordx4 v[194:195], off
	v_lshl_add_u64 v[194:195], v[120:121], 0, s[36:37]
	s_add_i32 m0, s58, 0xe000
	s_nop 0
	global_load_lds_dwordx4 v[194:195], off
	s_waitcnt vmcnt(8)
	s_waitcnt lgkmcnt(0)
	s_barrier
	s_setprio 1
	v_mfma_f32_16x16x32_bf16 v[154:157], v[126:129], v[166:169], v[154:157]
	v_mfma_f32_16x16x32_bf16 v[150:153], v[134:137], v[166:169], v[150:153]
	v_mfma_f32_16x16x32_bf16 v[110:113], v[126:129], v[174:177], v[110:113]
	v_mfma_f32_16x16x32_bf16 v[106:109], v[134:137], v[174:177], v[106:109]
	v_mfma_f32_16x16x32_bf16 v[94:97], v[126:129], v[182:185], v[94:97]
	v_mfma_f32_16x16x32_bf16 v[90:93], v[134:137], v[182:185], v[90:93]
	v_mfma_f32_16x16x32_bf16 v[78:81], v[126:129], v[208:211], v[78:81]
	v_mfma_f32_16x16x32_bf16 v[74:77], v[134:137], v[208:211], v[74:77]
	v_mfma_f32_16x16x32_bf16 v[154:157], v[130:133], v[170:173], v[154:157]
	v_mfma_f32_16x16x32_bf16 v[150:153], v[138:141], v[170:173], v[150:153]
	v_mfma_f32_16x16x32_bf16 v[110:113], v[130:133], v[178:181], v[110:113]
	v_mfma_f32_16x16x32_bf16 v[106:109], v[138:141], v[178:181], v[106:109]
	v_mfma_f32_16x16x32_bf16 v[94:97], v[130:133], v[186:189], v[94:97]
	v_mfma_f32_16x16x32_bf16 v[90:93], v[138:141], v[186:189], v[90:93]
	v_mfma_f32_16x16x32_bf16 v[78:81], v[130:133], v[212:215], v[78:81]
	v_mfma_f32_16x16x32_bf16 v[74:77], v[138:141], v[212:215], v[74:77]
	v_mfma_f32_16x16x32_bf16 v[122:125], v[142:145], v[166:169], v[122:125]
	v_mfma_f32_16x16x32_bf16 v[114:117], v[158:161], v[166:169], v[114:117]
	v_mfma_f32_16x16x32_bf16 v[102:105], v[142:145], v[174:177], v[102:105]
	v_mfma_f32_16x16x32_bf16 v[98:101], v[158:161], v[174:177], v[98:101]
	v_mfma_f32_16x16x32_bf16 v[86:89], v[142:145], v[182:185], v[86:89]
	v_mfma_f32_16x16x32_bf16 v[82:85], v[158:161], v[182:185], v[82:85]
	v_mfma_f32_16x16x32_bf16 v[70:73], v[142:145], v[208:211], v[70:73]
	v_mfma_f32_16x16x32_bf16 v[66:69], v[158:161], v[208:211], v[66:69]
	v_mfma_f32_16x16x32_bf16 v[122:125], v[146:149], v[170:173], v[122:125]
	v_mfma_f32_16x16x32_bf16 v[114:117], v[162:165], v[170:173], v[114:117]
	v_mfma_f32_16x16x32_bf16 v[102:105], v[146:149], v[178:181], v[102:105]
	v_mfma_f32_16x16x32_bf16 v[98:101], v[162:165], v[178:181], v[98:101]
	v_mfma_f32_16x16x32_bf16 v[86:89], v[146:149], v[186:189], v[86:89]
	v_mfma_f32_16x16x32_bf16 v[82:85], v[162:165], v[186:189], v[82:85]
	v_mfma_f32_16x16x32_bf16 v[70:73], v[146:149], v[212:215], v[70:73]
	v_mfma_f32_16x16x32_bf16 v[66:69], v[162:165], v[212:215], v[66:69]
	s_setprio 0
	s_barrier
	s_add_i32 s4, s85, s57
	v_lshl_add_u64 v[194:195], s[40:41], 0, v[0:1]
	s_mov_b32 m0, s4
	ds_read_b128 v[166:169], v242 offset:16384
	ds_read_b128 v[170:173], v242 offset:17408
	ds_read_b128 v[174:177], v242 offset:18432
	ds_read_b128 v[178:181], v242 offset:19456
	ds_read_b128 v[182:185], v242 offset:20480
	ds_read_b128 v[186:189], v242 offset:21504
	ds_read_b128 v[208:211], v242 offset:22528
	ds_read_b128 v[212:215], v242 offset:23552
	global_load_lds_dwordx4 v[194:195], off
	s_add_i32 m0, s4, 0x2000
	s_add_u32 s86, s40, 0x100000
	v_lshl_add_u64 v[198:199], s[40:41], 0, v[190:191]
	s_addc_u32 s87, s41, 0
	s_add_i32 s4, vcc_lo, s57
	global_load_lds_dwordx4 v[198:199], off
	v_lshl_add_u64 v[216:217], s[86:87], 0, v[0:1]
	s_mov_b32 m0, s4
	s_nop 0
	global_load_lds_dwordx4 v[216:217], off
	v_lshl_add_u64 v[216:217], s[86:87], 0, v[190:191]
	s_add_i32 m0, s4, 0x2000
	s_nop 0
	global_load_lds_dwordx4 v[216:217], off
	v_lshl_add_u64 v[216:217], s[42:43], 0, v[202:203]
	s_mov_b32 m0, s58
	s_nop 0
	global_load_lds_dwordx4 v[216:217], off
	v_lshl_add_u64 v[216:217], s[42:43], 0, v[192:193]
	s_mov_b32 m0, s59
	s_nop 0
	global_load_lds_dwordx4 v[216:217], off
	s_waitcnt vmcnt(8)
	s_waitcnt lgkmcnt(0)
	s_barrier
	s_setprio 1
	v_mfma_f32_16x16x32_bf16 v[62:65], v[126:129], v[166:169], v[62:65]
	v_mfma_f32_16x16x32_bf16 v[58:61], v[134:137], v[166:169], v[58:61]
	v_mfma_f32_16x16x32_bf16 v[46:49], v[126:129], v[174:177], v[46:49]
	v_mfma_f32_16x16x32_bf16 v[42:45], v[134:137], v[174:177], v[42:45]
	v_mfma_f32_16x16x32_bf16 v[30:33], v[126:129], v[182:185], v[30:33]
	v_mfma_f32_16x16x32_bf16 v[26:29], v[134:137], v[182:185], v[26:29]
	v_mfma_f32_16x16x32_bf16 v[14:17], v[126:129], v[208:211], v[14:17]
	v_mfma_f32_16x16x32_bf16 v[10:13], v[134:137], v[208:211], v[10:13]
	v_mfma_f32_16x16x32_bf16 v[62:65], v[130:133], v[170:173], v[62:65]
	v_mfma_f32_16x16x32_bf16 v[58:61], v[138:141], v[170:173], v[58:61]
	v_mfma_f32_16x16x32_bf16 v[46:49], v[130:133], v[178:181], v[46:49]
	v_mfma_f32_16x16x32_bf16 v[42:45], v[138:141], v[178:181], v[42:45]
	v_mfma_f32_16x16x32_bf16 v[30:33], v[130:133], v[186:189], v[30:33]
	v_mfma_f32_16x16x32_bf16 v[26:29], v[138:141], v[186:189], v[26:29]
	v_mfma_f32_16x16x32_bf16 v[14:17], v[130:133], v[212:215], v[14:17]
	v_mfma_f32_16x16x32_bf16 v[10:13], v[138:141], v[212:215], v[10:13]
	v_mfma_f32_16x16x32_bf16 v[54:57], v[142:145], v[166:169], v[54:57]
	v_mfma_f32_16x16x32_bf16 v[50:53], v[158:161], v[166:169], v[50:53]
	v_mfma_f32_16x16x32_bf16 v[38:41], v[142:145], v[174:177], v[38:41]
	v_mfma_f32_16x16x32_bf16 v[34:37], v[158:161], v[174:177], v[34:37]
	v_mfma_f32_16x16x32_bf16 v[22:25], v[142:145], v[182:185], v[22:25]
	v_mfma_f32_16x16x32_bf16 v[18:21], v[158:161], v[182:185], v[18:21]
	v_mfma_f32_16x16x32_bf16 v[6:9], v[142:145], v[208:211], v[6:9]
	v_mfma_f32_16x16x32_bf16 v[2:5], v[158:161], v[208:211], v[2:5]
	v_mfma_f32_16x16x32_bf16 v[54:57], v[146:149], v[170:173], v[54:57]
	v_mfma_f32_16x16x32_bf16 v[50:53], v[162:165], v[170:173], v[50:53]
	v_mfma_f32_16x16x32_bf16 v[38:41], v[146:149], v[178:181], v[38:41]
	v_mfma_f32_16x16x32_bf16 v[34:37], v[162:165], v[178:181], v[34:37]
	v_mfma_f32_16x16x32_bf16 v[22:25], v[146:149], v[186:189], v[22:25]
	v_mfma_f32_16x16x32_bf16 v[18:21], v[162:165], v[186:189], v[18:21]
	v_mfma_f32_16x16x32_bf16 v[6:9], v[146:149], v[212:215], v[6:9]
	v_mfma_f32_16x16x32_bf16 v[2:5], v[162:165], v[212:215], v[2:5]
	s_setprio 0
	s_barrier
	s_add_i32 s4, 0, 0x18000
	s_add_i32 s5, 0, 0x1c000
	v_add_u32_e32 v138, s4, v231
	v_add_u32_e32 v162, s5, v231
	ds_read_b128 v[126:129], v138
	ds_read_b128 v[130:133], v138 offset:1024
	ds_read_b128 v[134:137], v138 offset:2048
	ds_read_b128 v[138:141], v138 offset:3072
	ds_read_b128 v[142:145], v162
	ds_read_b128 v[146:149], v162 offset:1024
	ds_read_b128 v[158:161], v162 offset:2048
	ds_read_b128 v[162:165], v162 offset:3072
	s_add_u32 s42, s42, 0x100000
	s_addc_u32 s43, s43, 0
	s_mov_b32 m0, s65
	v_lshl_add_u64 v[216:217], s[42:43], 0, v[202:203]
	ds_read_b128 v[166:169], v242 offset:32768
	ds_read_b128 v[170:173], v242 offset:33792
	ds_read_b128 v[174:177], v242 offset:34816
	ds_read_b128 v[178:181], v242 offset:35840
	ds_read_b128 v[182:185], v242 offset:36864
	ds_read_b128 v[186:189], v242 offset:37888
	ds_read_b128 v[208:211], v242 offset:38912
	ds_read_b128 v[212:215], v242 offset:39936
	global_load_lds_dwordx4 v[216:217], off
	v_lshl_add_u64 v[216:217], s[42:43], 0, v[192:193]
	s_mov_b32 m0, s68
	s_nop 0
	global_load_lds_dwordx4 v[216:217], off
	s_waitcnt vmcnt(8)
	s_waitcnt lgkmcnt(0)
	s_barrier
	s_setprio 1
	v_mfma_f32_16x16x32_bf16 v[154:157], v[126:129], v[166:169], v[154:157]
	v_mfma_f32_16x16x32_bf16 v[150:153], v[134:137], v[166:169], v[150:153]
	v_mfma_f32_16x16x32_bf16 v[110:113], v[126:129], v[174:177], v[110:113]
	v_mfma_f32_16x16x32_bf16 v[106:109], v[134:137], v[174:177], v[106:109]
	v_mfma_f32_16x16x32_bf16 v[94:97], v[126:129], v[182:185], v[94:97]
	v_mfma_f32_16x16x32_bf16 v[90:93], v[134:137], v[182:185], v[90:93]
	v_mfma_f32_16x16x32_bf16 v[78:81], v[126:129], v[208:211], v[78:81]
	v_mfma_f32_16x16x32_bf16 v[74:77], v[134:137], v[208:211], v[74:77]
	v_mfma_f32_16x16x32_bf16 v[154:157], v[130:133], v[170:173], v[154:157]
	v_mfma_f32_16x16x32_bf16 v[150:153], v[138:141], v[170:173], v[150:153]
	v_mfma_f32_16x16x32_bf16 v[110:113], v[130:133], v[178:181], v[110:113]
	v_mfma_f32_16x16x32_bf16 v[106:109], v[138:141], v[178:181], v[106:109]
	v_mfma_f32_16x16x32_bf16 v[94:97], v[130:133], v[186:189], v[94:97]
	v_mfma_f32_16x16x32_bf16 v[90:93], v[138:141], v[186:189], v[90:93]
	v_mfma_f32_16x16x32_bf16 v[78:81], v[130:133], v[212:215], v[78:81]
	v_mfma_f32_16x16x32_bf16 v[74:77], v[138:141], v[212:215], v[74:77]
	v_mfma_f32_16x16x32_bf16 v[122:125], v[142:145], v[166:169], v[122:125]
	v_mfma_f32_16x16x32_bf16 v[114:117], v[158:161], v[166:169], v[114:117]
	v_mfma_f32_16x16x32_bf16 v[102:105], v[142:145], v[174:177], v[102:105]
	v_mfma_f32_16x16x32_bf16 v[98:101], v[158:161], v[174:177], v[98:101]
	v_mfma_f32_16x16x32_bf16 v[86:89], v[142:145], v[182:185], v[86:89]
	v_mfma_f32_16x16x32_bf16 v[82:85], v[158:161], v[182:185], v[82:85]
	v_mfma_f32_16x16x32_bf16 v[70:73], v[142:145], v[208:211], v[70:73]
	v_mfma_f32_16x16x32_bf16 v[66:69], v[158:161], v[208:211], v[66:69]
	v_mfma_f32_16x16x32_bf16 v[122:125], v[146:149], v[170:173], v[122:125]
	v_mfma_f32_16x16x32_bf16 v[114:117], v[162:165], v[170:173], v[114:117]
	v_mfma_f32_16x16x32_bf16 v[102:105], v[146:149], v[178:181], v[102:105]
	v_mfma_f32_16x16x32_bf16 v[98:101], v[162:165], v[178:181], v[98:101]
	v_mfma_f32_16x16x32_bf16 v[86:89], v[146:149], v[186:189], v[86:89]
	v_mfma_f32_16x16x32_bf16 v[82:85], v[162:165], v[186:189], v[82:85]
	v_mfma_f32_16x16x32_bf16 v[70:73], v[146:149], v[212:215], v[70:73]
	v_mfma_f32_16x16x32_bf16 v[66:69], v[162:165], v[212:215], v[66:69]
	s_setprio 0
	s_barrier
	s_add_i32 s4, s4, s57
	v_lshl_add_u64 v[194:195], v[194:195], 0, s[90:91]
	s_mov_b32 m0, s4
	ds_read_b128 v[166:169], v242 offset:49152
	ds_read_b128 v[170:173], v242 offset:50176
	ds_read_b128 v[174:177], v242 offset:51200
	ds_read_b128 v[178:181], v242 offset:52224
	ds_read_b128 v[182:185], v242 offset:53248
	ds_read_b128 v[186:189], v242 offset:54272
	ds_read_b128 v[208:211], v242 offset:55296
	ds_read_b128 v[212:215], v242 offset:56320
	global_load_lds_dwordx4 v[194:195], off
	s_add_i32 m0, s4, 0x2000
	s_add_u32 s40, s40, 0x100080
	v_lshl_add_u64 v[194:195], v[198:199], 0, s[90:91]
	s_addc_u32 s41, s41, 0
	s_add_i32 s4, s5, s57
	global_load_lds_dwordx4 v[194:195], off
	v_lshl_add_u64 v[194:195], s[40:41], 0, v[0:1]
	s_mov_b32 m0, s4
	s_nop 0
	global_load_lds_dwordx4 v[194:195], off
	v_lshl_add_u64 v[194:195], s[40:41], 0, v[190:191]
	s_add_i32 m0, s4, 0x2000
	s_nop 0
	global_load_lds_dwordx4 v[194:195], off
	v_lshl_add_u64 v[194:195], s[38:39], 0, v[202:203]
	s_mov_b32 m0, s54
	s_nop 0
	global_load_lds_dwordx4 v[194:195], off
	v_lshl_add_u64 v[194:195], s[38:39], 0, v[192:193]
	s_mov_b32 m0, s55
	s_nop 0
	global_load_lds_dwordx4 v[194:195], off
	s_waitcnt vmcnt(8)
	s_waitcnt lgkmcnt(0)
	s_barrier
	s_setprio 1
	v_mfma_f32_16x16x32_bf16 v[62:65], v[126:129], v[166:169], v[62:65]
	v_mfma_f32_16x16x32_bf16 v[58:61], v[134:137], v[166:169], v[58:61]
	v_mfma_f32_16x16x32_bf16 v[46:49], v[126:129], v[174:177], v[46:49]
	v_mfma_f32_16x16x32_bf16 v[42:45], v[134:137], v[174:177], v[42:45]
	v_mfma_f32_16x16x32_bf16 v[30:33], v[126:129], v[182:185], v[30:33]
	v_mfma_f32_16x16x32_bf16 v[26:29], v[134:137], v[182:185], v[26:29]
	v_mfma_f32_16x16x32_bf16 v[14:17], v[126:129], v[208:211], v[14:17]
	v_mfma_f32_16x16x32_bf16 v[10:13], v[134:137], v[208:211], v[10:13]
	v_mfma_f32_16x16x32_bf16 v[62:65], v[130:133], v[170:173], v[62:65]
	v_mfma_f32_16x16x32_bf16 v[58:61], v[138:141], v[170:173], v[58:61]
	v_mfma_f32_16x16x32_bf16 v[46:49], v[130:133], v[178:181], v[46:49]
	v_mfma_f32_16x16x32_bf16 v[42:45], v[138:141], v[178:181], v[42:45]
	v_mfma_f32_16x16x32_bf16 v[30:33], v[130:133], v[186:189], v[30:33]
	v_mfma_f32_16x16x32_bf16 v[26:29], v[138:141], v[186:189], v[26:29]
	v_mfma_f32_16x16x32_bf16 v[14:17], v[130:133], v[212:215], v[14:17]
	v_mfma_f32_16x16x32_bf16 v[10:13], v[138:141], v[212:215], v[10:13]
	v_mfma_f32_16x16x32_bf16 v[54:57], v[142:145], v[166:169], v[54:57]
	v_mfma_f32_16x16x32_bf16 v[50:53], v[158:161], v[166:169], v[50:53]
	v_mfma_f32_16x16x32_bf16 v[38:41], v[142:145], v[174:177], v[38:41]
	v_mfma_f32_16x16x32_bf16 v[34:37], v[158:161], v[174:177], v[34:37]
	v_mfma_f32_16x16x32_bf16 v[22:25], v[142:145], v[182:185], v[22:25]
	v_mfma_f32_16x16x32_bf16 v[18:21], v[158:161], v[182:185], v[18:21]
	v_mfma_f32_16x16x32_bf16 v[6:9], v[142:145], v[208:211], v[6:9]
	v_mfma_f32_16x16x32_bf16 v[2:5], v[158:161], v[208:211], v[2:5]
	v_mfma_f32_16x16x32_bf16 v[54:57], v[146:149], v[170:173], v[54:57]
	v_mfma_f32_16x16x32_bf16 v[50:53], v[162:165], v[170:173], v[50:53]
	v_mfma_f32_16x16x32_bf16 v[38:41], v[146:149], v[178:181], v[38:41]
	v_mfma_f32_16x16x32_bf16 v[34:37], v[162:165], v[178:181], v[34:37]
	v_mfma_f32_16x16x32_bf16 v[22:25], v[146:149], v[186:189], v[22:25]
	v_mfma_f32_16x16x32_bf16 v[18:21], v[162:165], v[186:189], v[18:21]
	v_mfma_f32_16x16x32_bf16 v[6:9], v[146:149], v[212:215], v[6:9]
	v_mfma_f32_16x16x32_bf16 v[2:5], v[162:165], v[212:215], v[2:5]
	s_setprio 0
	s_barrier
	s_add_i32 s84, s84, 2
	s_add_u32 s36, s36, 0x100
	s_addc_u32 s37, s37, 0
	s_cmp_gt_u32 s84, 61
	s_cbranch_scc0 .LBB0_915
	s_and_b64 vcc, exec, s[20:21]
	s_cbranch_vccz .LBB0_918
	s_barrier

.LBB0_953:
	s_add_u32 s4, s24, s26
	s_addc_u32 s5, s25, s27
	s_add_u32 s34, s4, 0x100
	s_addc_u32 s35, s5, 0
	s_add_u32 s30, s68, s26
	s_addc_u32 s31, s69, s27
	s_add_u32 s4, s4, 0x180
	s_addc_u32 s5, s5, 0
	s_add_i32 s71, 0, 0x10000
	s_add_i32 s74, 0, 0x14000
	v_add_u32_e32 v146, s71, v229
	v_add_u32_e32 v162, s74, v229
	ds_read_b128 v[134:137], v146
	ds_read_b128 v[138:141], v146 offset:1024
	ds_read_b128 v[142:145], v146 offset:2048
	ds_read_b128 v[146:149], v146 offset:3072
	ds_read_b128 v[150:153], v162
	ds_read_b128 v[154:157], v162 offset:1024
	ds_read_b128 v[158:161], v162 offset:2048
	ds_read_b128 v[162:165], v162 offset:3072
	s_cmpk_eq_i32 s26, 0x1f00
	s_cselect_b32 s29, s65, s5
	s_cselect_b32 s28, s59, s4
	s_cselect_b32 s31, s17, s31
	s_cselect_b32 s30, s58, s30
	s_cselect_b32 s35, s19, s35
	s_cselect_b32 s34, s57, s34
	v_lshl_add_u64 v[194:195], v[122:123], 0, s[26:27]
	s_add_i32 m0, s37, 0xc000
	ds_read_b128 v[166:169], v231
	ds_read_b128 v[170:173], v231 offset:1024
	ds_read_b128 v[174:177], v231 offset:2048
	ds_read_b128 v[178:181], v231 offset:3072
	ds_read_b128 v[182:185], v231 offset:4096
	ds_read_b128 v[186:189], v231 offset:5120
	ds_read_b128 v[190:193], v231 offset:6144
	ds_read_b128 v[212:215], v231 offset:7168
	global_load_lds_dwordx4 v[194:195], off
	v_lshl_add_u64 v[194:195], v[124:125], 0, s[26:27]
	s_add_i32 m0, s37, 0xe000
	s_nop 0
	global_load_lds_dwordx4 v[194:195], off
	s_waitcnt vmcnt(8)
	s_waitcnt lgkmcnt(0)
	s_barrier
	s_setprio 1
	v_mfma_f32_16x16x32_bf16 v[130:133], v[134:137], v[166:169], v[130:133]
	v_mfma_f32_16x16x32_bf16 v[126:129], v[142:145], v[166:169], v[126:129]
	v_mfma_f32_16x16x32_bf16 v[110:113], v[134:137], v[174:177], v[110:113]
	v_mfma_f32_16x16x32_bf16 v[106:109], v[142:145], v[174:177], v[106:109]
	v_mfma_f32_16x16x32_bf16 v[94:97], v[134:137], v[182:185], v[94:97]
	v_mfma_f32_16x16x32_bf16 v[90:93], v[142:145], v[182:185], v[90:93]
	v_mfma_f32_16x16x32_bf16 v[78:81], v[134:137], v[190:193], v[78:81]
	v_mfma_f32_16x16x32_bf16 v[74:77], v[142:145], v[190:193], v[74:77]
	v_mfma_f32_16x16x32_bf16 v[130:133], v[138:141], v[170:173], v[130:133]
	v_mfma_f32_16x16x32_bf16 v[126:129], v[146:149], v[170:173], v[126:129]
	v_mfma_f32_16x16x32_bf16 v[110:113], v[138:141], v[178:181], v[110:113]
	v_mfma_f32_16x16x32_bf16 v[106:109], v[146:149], v[178:181], v[106:109]
	v_mfma_f32_16x16x32_bf16 v[94:97], v[138:141], v[186:189], v[94:97]
	v_mfma_f32_16x16x32_bf16 v[90:93], v[146:149], v[186:189], v[90:93]
	v_mfma_f32_16x16x32_bf16 v[78:81], v[138:141], v[212:215], v[78:81]
	v_mfma_f32_16x16x32_bf16 v[74:77], v[146:149], v[212:215], v[74:77]
	v_mfma_f32_16x16x32_bf16 v[118:121], v[150:153], v[166:169], v[118:121]
	v_mfma_f32_16x16x32_bf16 v[114:117], v[158:161], v[166:169], v[114:117]
	v_mfma_f32_16x16x32_bf16 v[102:105], v[150:153], v[174:177], v[102:105]
	v_mfma_f32_16x16x32_bf16 v[98:101], v[158:161], v[174:177], v[98:101]
	v_mfma_f32_16x16x32_bf16 v[86:89], v[150:153], v[182:185], v[86:89]
	v_mfma_f32_16x16x32_bf16 v[82:85], v[158:161], v[182:185], v[82:85]
	v_mfma_f32_16x16x32_bf16 v[70:73], v[150:153], v[190:193], v[70:73]
	v_mfma_f32_16x16x32_bf16 v[66:69], v[158:161], v[190:193], v[66:69]
	v_mfma_f32_16x16x32_bf16 v[118:121], v[154:157], v[170:173], v[118:121]
	v_mfma_f32_16x16x32_bf16 v[114:117], v[162:165], v[170:173], v[114:117]
	v_mfma_f32_16x16x32_bf16 v[102:105], v[154:157], v[178:181], v[102:105]
	v_mfma_f32_16x16x32_bf16 v[98:101], v[162:165], v[178:181], v[98:101]
	v_mfma_f32_16x16x32_bf16 v[86:89], v[154:157], v[186:189], v[86:89]
	v_mfma_f32_16x16x32_bf16 v[82:85], v[162:165], v[186:189], v[82:85]
	v_mfma_f32_16x16x32_bf16 v[70:73], v[154:157], v[212:215], v[70:73]
	v_mfma_f32_16x16x32_bf16 v[66:69], v[162:165], v[212:215], v[66:69]
	s_setprio 0
	s_barrier
	s_add_i32 s4, s71, s36
	v_lshl_add_u64 v[194:195], s[30:31], 0, v[0:1]
	s_mov_b32 m0, s4
	ds_read_b128 v[166:169], v231 offset:16384
	ds_read_b128 v[170:173], v231 offset:17408
	ds_read_b128 v[174:177], v231 offset:18432
	ds_read_b128 v[178:181], v231 offset:19456
	ds_read_b128 v[182:185], v231 offset:20480
	ds_read_b128 v[186:189], v231 offset:21504
	ds_read_b128 v[190:193], v231 offset:22528
	ds_read_b128 v[212:215], v231 offset:23552
	global_load_lds_dwordx4 v[194:195], off
	s_add_i32 m0, s4, 0x2000
	s_add_u32 s72, s30, 0x100000
	v_lshl_add_u64 v[198:199], s[30:31], 0, v[202:203]
	s_addc_u32 s73, s31, 0
	s_add_i32 s4, s74, s36
	global_load_lds_dwordx4 v[198:199], off
	v_lshl_add_u64 v[216:217], s[72:73], 0, v[0:1]
	s_mov_b32 m0, s4
	s_nop 0
	global_load_lds_dwordx4 v[216:217], off
	v_lshl_add_u64 v[216:217], s[72:73], 0, v[202:203]
	s_add_i32 m0, s4, 0x2000
	s_nop 0
	global_load_lds_dwordx4 v[216:217], off
	v_lshl_add_u64 v[216:217], s[34:35], 0, v[206:207]
	s_mov_b32 m0, s37
	s_nop 0
	global_load_lds_dwordx4 v[216:217], off
	v_lshl_add_u64 v[216:217], s[34:35], 0, v[204:205]
	s_mov_b32 m0, s38
	s_nop 0
	global_load_lds_dwordx4 v[216:217], off
	s_waitcnt vmcnt(8)
	s_waitcnt lgkmcnt(0)
	s_barrier
	s_setprio 1
	v_mfma_f32_16x16x32_bf16 v[62:65], v[134:137], v[166:169], v[62:65]
	v_mfma_f32_16x16x32_bf16 v[58:61], v[142:145], v[166:169], v[58:61]
	v_mfma_f32_16x16x32_bf16 v[46:49], v[134:137], v[174:177], v[46:49]
	v_mfma_f32_16x16x32_bf16 v[42:45], v[142:145], v[174:177], v[42:45]
	v_mfma_f32_16x16x32_bf16 v[30:33], v[134:137], v[182:185], v[30:33]
	v_mfma_f32_16x16x32_bf16 v[26:29], v[142:145], v[182:185], v[26:29]
	v_mfma_f32_16x16x32_bf16 v[14:17], v[134:137], v[190:193], v[14:17]
	v_mfma_f32_16x16x32_bf16 v[10:13], v[142:145], v[190:193], v[10:13]
	v_mfma_f32_16x16x32_bf16 v[62:65], v[138:141], v[170:173], v[62:65]
	v_mfma_f32_16x16x32_bf16 v[58:61], v[146:149], v[170:173], v[58:61]
	v_mfma_f32_16x16x32_bf16 v[46:49], v[138:141], v[178:181], v[46:49]
	v_mfma_f32_16x16x32_bf16 v[42:45], v[146:149], v[178:181], v[42:45]
	v_mfma_f32_16x16x32_bf16 v[30:33], v[138:141], v[186:189], v[30:33]
	v_mfma_f32_16x16x32_bf16 v[26:29], v[146:149], v[186:189], v[26:29]
	v_mfma_f32_16x16x32_bf16 v[14:17], v[138:141], v[212:215], v[14:17]
	v_mfma_f32_16x16x32_bf16 v[10:13], v[146:149], v[212:215], v[10:13]
	v_mfma_f32_16x16x32_bf16 v[54:57], v[150:153], v[166:169], v[54:57]
	v_mfma_f32_16x16x32_bf16 v[50:53], v[158:161], v[166:169], v[50:53]
	v_mfma_f32_16x16x32_bf16 v[38:41], v[150:153], v[174:177], v[38:41]
	v_mfma_f32_16x16x32_bf16 v[34:37], v[158:161], v[174:177], v[34:37]
	v_mfma_f32_16x16x32_bf16 v[22:25], v[150:153], v[182:185], v[22:25]
	v_mfma_f32_16x16x32_bf16 v[18:21], v[158:161], v[182:185], v[18:21]
	v_mfma_f32_16x16x32_bf16 v[6:9], v[150:153], v[190:193], v[6:9]
	v_mfma_f32_16x16x32_bf16 v[2:5], v[158:161], v[190:193], v[2:5]
	v_mfma_f32_16x16x32_bf16 v[54:57], v[154:157], v[170:173], v[54:57]
	v_mfma_f32_16x16x32_bf16 v[50:53], v[162:165], v[170:173], v[50:53]
	v_mfma_f32_16x16x32_bf16 v[38:41], v[154:157], v[178:181], v[38:41]
	v_mfma_f32_16x16x32_bf16 v[34:37], v[162:165], v[178:181], v[34:37]
	v_mfma_f32_16x16x32_bf16 v[22:25], v[154:157], v[186:189], v[22:25]
	v_mfma_f32_16x16x32_bf16 v[18:21], v[162:165], v[186:189], v[18:21]
	v_mfma_f32_16x16x32_bf16 v[6:9], v[154:157], v[212:215], v[6:9]
	v_mfma_f32_16x16x32_bf16 v[2:5], v[162:165], v[212:215], v[2:5]
	s_setprio 0
	s_barrier
	s_add_i32 s4, 0, 0x18000
	s_add_i32 s5, 0, 0x1c000
	v_add_u32_e32 v146, s4, v229
	v_add_u32_e32 v162, s5, v229
	ds_read_b128 v[134:137], v146
	ds_read_b128 v[138:141], v146 offset:1024
	ds_read_b128 v[142:145], v146 offset:2048
	ds_read_b128 v[146:149], v146 offset:3072
	ds_read_b128 v[150:153], v162
	ds_read_b128 v[154:157], v162 offset:1024
	ds_read_b128 v[158:161], v162 offset:2048
	ds_read_b128 v[162:165], v162 offset:3072
	s_add_u32 s34, s34, 0x100000
	s_addc_u32 s35, s35, 0
	s_mov_b32 m0, s39
	v_lshl_add_u64 v[216:217], s[34:35], 0, v[206:207]
	ds_read_b128 v[166:169], v231 offset:32768
	ds_read_b128 v[170:173], v231 offset:33792
	ds_read_b128 v[174:177], v231 offset:34816
	ds_read_b128 v[178:181], v231 offset:35840
	ds_read_b128 v[182:185], v231 offset:36864
	ds_read_b128 v[186:189], v231 offset:37888
	ds_read_b128 v[190:193], v231 offset:38912
	ds_read_b128 v[212:215], v231 offset:39936
	global_load_lds_dwordx4 v[216:217], off
	v_lshl_add_u64 v[216:217], s[34:35], 0, v[204:205]
	s_mov_b32 m0, s40
	s_nop 0
	global_load_lds_dwordx4 v[216:217], off
	s_waitcnt vmcnt(8)
	s_waitcnt lgkmcnt(0)
	s_barrier
	s_setprio 1
	v_mfma_f32_16x16x32_bf16 v[130:133], v[134:137], v[166:169], v[130:133]
	v_mfma_f32_16x16x32_bf16 v[126:129], v[142:145], v[166:169], v[126:129]
	v_mfma_f32_16x16x32_bf16 v[110:113], v[134:137], v[174:177], v[110:113]
	v_mfma_f32_16x16x32_bf16 v[106:109], v[142:145], v[174:177], v[106:109]
	v_mfma_f32_16x16x32_bf16 v[94:97], v[134:137], v[182:185], v[94:97]
	v_mfma_f32_16x16x32_bf16 v[90:93], v[142:145], v[182:185], v[90:93]
	v_mfma_f32_16x16x32_bf16 v[78:81], v[134:137], v[190:193], v[78:81]
	v_mfma_f32_16x16x32_bf16 v[74:77], v[142:145], v[190:193], v[74:77]
	v_mfma_f32_16x16x32_bf16 v[130:133], v[138:141], v[170:173], v[130:133]
	v_mfma_f32_16x16x32_bf16 v[126:129], v[146:149], v[170:173], v[126:129]
	v_mfma_f32_16x16x32_bf16 v[110:113], v[138:141], v[178:181], v[110:113]
	v_mfma_f32_16x16x32_bf16 v[106:109], v[146:149], v[178:181], v[106:109]
	v_mfma_f32_16x16x32_bf16 v[94:97], v[138:141], v[186:189], v[94:97]
	v_mfma_f32_16x16x32_bf16 v[90:93], v[146:149], v[186:189], v[90:93]
	v_mfma_f32_16x16x32_bf16 v[78:81], v[138:141], v[212:215], v[78:81]
	v_mfma_f32_16x16x32_bf16 v[74:77], v[146:149], v[212:215], v[74:77]
	v_mfma_f32_16x16x32_bf16 v[118:121], v[150:153], v[166:169], v[118:121]
	v_mfma_f32_16x16x32_bf16 v[114:117], v[158:161], v[166:169], v[114:117]
	v_mfma_f32_16x16x32_bf16 v[102:105], v[150:153], v[174:177], v[102:105]
	v_mfma_f32_16x16x32_bf16 v[98:101], v[158:161], v[174:177], v[98:101]
	v_mfma_f32_16x16x32_bf16 v[86:89], v[150:153], v[182:185], v[86:89]
	v_mfma_f32_16x16x32_bf16 v[82:85], v[158:161], v[182:185], v[82:85]
	v_mfma_f32_16x16x32_bf16 v[70:73], v[150:153], v[190:193], v[70:73]
	v_mfma_f32_16x16x32_bf16 v[66:69], v[158:161], v[190:193], v[66:69]
	v_mfma_f32_16x16x32_bf16 v[118:121], v[154:157], v[170:173], v[118:121]
	v_mfma_f32_16x16x32_bf16 v[114:117], v[162:165], v[170:173], v[114:117]
	v_mfma_f32_16x16x32_bf16 v[102:105], v[154:157], v[178:181], v[102:105]
	v_mfma_f32_16x16x32_bf16 v[98:101], v[162:165], v[178:181], v[98:101]
	v_mfma_f32_16x16x32_bf16 v[86:89], v[154:157], v[186:189], v[86:89]
	v_mfma_f32_16x16x32_bf16 v[82:85], v[162:165], v[186:189], v[82:85]
	v_mfma_f32_16x16x32_bf16 v[70:73], v[154:157], v[212:215], v[70:73]
	v_mfma_f32_16x16x32_bf16 v[66:69], v[162:165], v[212:215], v[66:69]
	s_setprio 0
	s_barrier
	s_add_i32 s4, s4, s36
	v_lshl_add_u64 v[194:195], v[194:195], 0, s[90:91]
	s_mov_b32 m0, s4
	ds_read_b128 v[166:169], v231 offset:49152
	ds_read_b128 v[170:173], v231 offset:50176
	ds_read_b128 v[174:177], v231 offset:51200
	ds_read_b128 v[178:181], v231 offset:52224
	ds_read_b128 v[182:185], v231 offset:53248
	ds_read_b128 v[186:189], v231 offset:54272
	ds_read_b128 v[190:193], v231 offset:55296
	ds_read_b128 v[212:215], v231 offset:56320
	global_load_lds_dwordx4 v[194:195], off
	s_add_i32 m0, s4, 0x2000
	s_add_u32 s30, s30, 0x100080
	v_lshl_add_u64 v[194:195], v[198:199], 0, s[90:91]
	s_addc_u32 s31, s31, 0
	s_add_i32 s4, s5, s36
	global_load_lds_dwordx4 v[194:195], off
	v_lshl_add_u64 v[194:195], s[30:31], 0, v[0:1]
	s_mov_b32 m0, s4
	s_nop 0
	global_load_lds_dwordx4 v[194:195], off
	v_lshl_add_u64 v[194:195], s[30:31], 0, v[202:203]
	s_add_i32 m0, s4, 0x2000
	s_nop 0
	global_load_lds_dwordx4 v[194:195], off
	v_lshl_add_u64 v[194:195], s[28:29], 0, v[206:207]
	s_mov_b32 m0, s41
	s_nop 0
	global_load_lds_dwordx4 v[194:195], off
	v_lshl_add_u64 v[194:195], s[28:29], 0, v[204:205]
	s_mov_b32 m0, s42
	s_nop 0
	global_load_lds_dwordx4 v[194:195], off
	s_waitcnt vmcnt(8)
	s_waitcnt lgkmcnt(0)
	s_barrier
	s_setprio 1
	v_mfma_f32_16x16x32_bf16 v[62:65], v[134:137], v[166:169], v[62:65]
	v_mfma_f32_16x16x32_bf16 v[58:61], v[142:145], v[166:169], v[58:61]
	v_mfma_f32_16x16x32_bf16 v[46:49], v[134:137], v[174:177], v[46:49]
	v_mfma_f32_16x16x32_bf16 v[42:45], v[142:145], v[174:177], v[42:45]
	v_mfma_f32_16x16x32_bf16 v[30:33], v[134:137], v[182:185], v[30:33]
	v_mfma_f32_16x16x32_bf16 v[26:29], v[142:145], v[182:185], v[26:29]
	v_mfma_f32_16x16x32_bf16 v[14:17], v[134:137], v[190:193], v[14:17]
	v_mfma_f32_16x16x32_bf16 v[10:13], v[142:145], v[190:193], v[10:13]
	v_mfma_f32_16x16x32_bf16 v[62:65], v[138:141], v[170:173], v[62:65]
	v_mfma_f32_16x16x32_bf16 v[58:61], v[146:149], v[170:173], v[58:61]
	v_mfma_f32_16x16x32_bf16 v[46:49], v[138:141], v[178:181], v[46:49]
	v_mfma_f32_16x16x32_bf16 v[42:45], v[146:149], v[178:181], v[42:45]
	v_mfma_f32_16x16x32_bf16 v[30:33], v[138:141], v[186:189], v[30:33]
	v_mfma_f32_16x16x32_bf16 v[26:29], v[146:149], v[186:189], v[26:29]
	v_mfma_f32_16x16x32_bf16 v[14:17], v[138:141], v[212:215], v[14:17]
	v_mfma_f32_16x16x32_bf16 v[10:13], v[146:149], v[212:215], v[10:13]
	v_mfma_f32_16x16x32_bf16 v[54:57], v[150:153], v[166:169], v[54:57]
	v_mfma_f32_16x16x32_bf16 v[50:53], v[158:161], v[166:169], v[50:53]
	v_mfma_f32_16x16x32_bf16 v[38:41], v[150:153], v[174:177], v[38:41]
	v_mfma_f32_16x16x32_bf16 v[34:37], v[158:161], v[174:177], v[34:37]
	v_mfma_f32_16x16x32_bf16 v[22:25], v[150:153], v[182:185], v[22:25]
	v_mfma_f32_16x16x32_bf16 v[18:21], v[158:161], v[182:185], v[18:21]
	v_mfma_f32_16x16x32_bf16 v[6:9], v[150:153], v[190:193], v[6:9]
	v_mfma_f32_16x16x32_bf16 v[2:5], v[158:161], v[190:193], v[2:5]
	v_mfma_f32_16x16x32_bf16 v[54:57], v[154:157], v[170:173], v[54:57]
	v_mfma_f32_16x16x32_bf16 v[50:53], v[162:165], v[170:173], v[50:53]
	v_mfma_f32_16x16x32_bf16 v[38:41], v[154:157], v[178:181], v[38:41]
	v_mfma_f32_16x16x32_bf16 v[34:37], v[162:165], v[178:181], v[34:37]
	v_mfma_f32_16x16x32_bf16 v[22:25], v[154:157], v[186:189], v[22:25]
	v_mfma_f32_16x16x32_bf16 v[18:21], v[162:165], v[186:189], v[18:21]
	v_mfma_f32_16x16x32_bf16 v[6:9], v[154:157], v[212:215], v[6:9]
	v_mfma_f32_16x16x32_bf16 v[2:5], v[162:165], v[212:215], v[2:5]
	s_setprio 0
	s_barrier
	s_add_i32 s70, s70, 2
	s_add_u32 s26, s26, 0x100
	s_addc_u32 s27, s27, 0
	s_cmp_gt_u32 s70, 61
	s_cbranch_scc0 .LBB0_953
	s_and_b64 vcc, exec, s[14:15]
	s_cbranch_vccz .LBB0_956
	s_barrier
